# GEMM K-loops: deleted 16 provably redundant s_waitcnt lgkmcnt(0) issued right before each phase's first MFMA
# speedup vs baseline: 1.0092x; 1.0092x over previous
; #define PG8_STAGE(bufoff, gbase, voff) do { _Pragma("unroll") for (int _i = 0; _i < 2; ++_i) \
;         __builtin_amdgcn_global_load_lds((const unsigned*)((const char*)(gbase) + (voff)[_i]), (LAS unsigned*)(lds + (bufoff) + ldsw + _i * 8192), 16, 0, 0); } while (0)
; #define PG8_LDA(dst, b, h) do { _Pragma("unroll") for (int m = 0; m < 4; ++m) _Pragma("unroll") for (int k = 0; k < 2; ++k) dst[m][k] = *(const LAS bf16x8*)(lds + PG8_SA(b, h) + aoff + m * 2048 + k * 1024); } while (0)
; #define PG8_LDB(dst, b, h) do { _Pragma("unroll") for (int n = 0; n < 2; ++n) _Pragma("unroll") for (int k = 0; k < 2; ++k) dst[n][k] = *(const LAS bf16x8*)(lds + PG8_SB(b, h) + boff + n * 2048 + k * 1024); } while (0)
; #define PG8_MMA(ai, bj, At, Bt) do { __builtin_amdgcn_s_setprio(1); _Pragma("unroll") for (int m = 0; m < 4; ++m) _Pragma("unroll") for (int n = 0; n < 2; ++n) _Pragma("unroll") for (int k = 0; k < 2; ++k) \
;         acc[ai][bj][m][n] = __builtin_amdgcn_mfma_f32_16x16x32_bf16(Bt[n][k], At[m][k], acc[ai][bj][m][n], 0, 0, 0); __builtin_amdgcn_s_setprio(0); } while (0)
; #define PG8_WAIT_V(n) asm volatile("s_waitcnt vmcnt(" #n ")" ::: "memory")
; #define PG8_WAIT_L(n) asm volatile("s_waitcnt lgkmcnt(" #n ")" ::: "memory")
; #define PG8_BAR __builtin_amdgcn_s_barrier()
; #define PG8_SCHED __builtin_amdgcn_sched_barrier(0)
; template <class Epi>
; __device__ __forceinline__ void gemm_phase(LAS unsigned char* lds, const Gemm g, const StaticOrder& S, const Epi& E) {
;     ...
;             PG8_LDB(B0, 0, 0); PG8_LDB(B1, 0, 1); PG8_SCHED; PG8_LDA(At, 0, 0); PG8_STAGE(PG8_SA(1, 1), a1 + hstepA, voffA);
;             PG8_WAIT_V(8); PG8_WAIT_L(0); PG8_BAR; PG8_MMA(0, 0, At, B0); PG8_MMA(0, 1, At, B1); PG8_BAR; PG8_SCHED;
;             PG8_LDA(At, 0, 1); PG8_STAGE(PG8_SB(0, 0), b2, voffB); PG8_STAGE(PG8_SB(0, 1), b2 + hstepB, voffB); PG8_STAGE(PG8_SA(0, 0), a2, voffA);
;             PG8_WAIT_V(8); PG8_WAIT_L(0); PG8_BAR; PG8_MMA(1, 0, At, B0); PG8_MMA(1, 1, At, B1); PG8_BAR; PG8_SCHED;
.LBB0_187:
	s_add_i32 s16, s15, 2
	s_add_u32 s17, s0, 0xfff70080
	s_addc_u32 s18, s1, -1
	s_add_i32 s20, 0, 0x10000
	s_cmp_eq_u32 s81, s15
	s_cselect_b32 s41, s91, s18
	s_cselect_b32 s40, s90, s17
	v_add_u32_e32 v0, s20, v157
	s_cselect_b32 s19, s93, s14
	s_cselect_b32 s18, s92, s13
	s_add_i32 s15, 0, 0x14000
	ds_read_b128 v[142:145], v0
	ds_read_b128 v[146:149], v0 offset:1024
	ds_read_b128 v[150:153], v0 offset:2048
	ds_read_b128 v[160:163], v0 offset:3072
	v_add_u32_e32 v0, s15, v157
	ds_read_b128 v[164:167], v0
	ds_read_b128 v[168:171], v0 offset:1024
	ds_read_b128 v[172:175], v0 offset:2048
	ds_read_b128 v[176:179], v0 offset:3072
	v_lshl_add_u64 v[214:215], s[0:1], 0, v[140:141]
	s_add_i32 m0, s53, 0xc000
	ds_read_b128 v[182:185], v159
	ds_read_b128 v[186:189], v159 offset:1024
	ds_read_b128 v[190:193], v159 offset:2048
	ds_read_b128 v[194:197], v159 offset:3072
	ds_read_b128 v[198:201], v159 offset:4096
	ds_read_b128 v[202:205], v159 offset:5120
	ds_read_b128 v[206:209], v159 offset:6144
	ds_read_b128 v[210:213], v159 offset:7168
	global_load_lds_dwordx4 v[214:215], off
	v_lshl_add_u64 v[214:215], s[0:1], 0, v[138:139]
	s_add_i32 m0, s53, 0xe000
	s_nop 0
	global_load_lds_dwordx4 v[214:215], off
	s_waitcnt vmcnt(8)
	s_waitcnt lgkmcnt(0)
	s_barrier
	s_setprio 1
	v_mfma_f32_16x16x32_bf16 v[126:129], v[142:145], v[182:185], v[126:129]
	v_mfma_f32_16x16x32_bf16 v[122:125], v[150:153], v[182:185], v[122:125]
	v_mfma_f32_16x16x32_bf16 v[110:113], v[142:145], v[190:193], v[110:113]
	v_mfma_f32_16x16x32_bf16 v[106:109], v[150:153], v[190:193], v[106:109]
	v_mfma_f32_16x16x32_bf16 v[94:97], v[142:145], v[198:201], v[94:97]
	v_mfma_f32_16x16x32_bf16 v[90:93], v[150:153], v[198:201], v[90:93]
	v_mfma_f32_16x16x32_bf16 v[78:81], v[142:145], v[206:209], v[78:81]
	v_mfma_f32_16x16x32_bf16 v[74:77], v[150:153], v[206:209], v[74:77]
	v_mfma_f32_16x16x32_bf16 v[126:129], v[146:149], v[186:189], v[126:129]
	v_mfma_f32_16x16x32_bf16 v[122:125], v[160:163], v[186:189], v[122:125]
	v_mfma_f32_16x16x32_bf16 v[110:113], v[146:149], v[194:197], v[110:113]
	v_mfma_f32_16x16x32_bf16 v[106:109], v[160:163], v[194:197], v[106:109]
	v_mfma_f32_16x16x32_bf16 v[94:97], v[146:149], v[202:205], v[94:97]
	v_mfma_f32_16x16x32_bf16 v[90:93], v[160:163], v[202:205], v[90:93]
	v_mfma_f32_16x16x32_bf16 v[78:81], v[146:149], v[210:213], v[78:81]
	v_mfma_f32_16x16x32_bf16 v[74:77], v[160:163], v[210:213], v[74:77]
	s_setprio 0
	s_setprio 1
	v_mfma_f32_16x16x32_bf16 v[118:121], v[164:167], v[182:185], v[118:121]
	v_mfma_f32_16x16x32_bf16 v[114:117], v[172:175], v[182:185], v[114:117]
	v_mfma_f32_16x16x32_bf16 v[102:105], v[164:167], v[190:193], v[102:105]
	v_mfma_f32_16x16x32_bf16 v[98:101], v[172:175], v[190:193], v[98:101]
	v_mfma_f32_16x16x32_bf16 v[86:89], v[164:167], v[198:201], v[86:89]
	v_mfma_f32_16x16x32_bf16 v[82:85], v[172:175], v[198:201], v[82:85]
	v_mfma_f32_16x16x32_bf16 v[70:73], v[164:167], v[206:209], v[70:73]
	v_mfma_f32_16x16x32_bf16 v[66:69], v[172:175], v[206:209], v[66:69]
	v_mfma_f32_16x16x32_bf16 v[118:121], v[168:171], v[186:189], v[118:121]
	v_mfma_f32_16x16x32_bf16 v[114:117], v[176:179], v[186:189], v[114:117]
	v_mfma_f32_16x16x32_bf16 v[102:105], v[168:171], v[194:197], v[102:105]
	v_mfma_f32_16x16x32_bf16 v[98:101], v[176:179], v[194:197], v[98:101]
	v_mfma_f32_16x16x32_bf16 v[86:89], v[168:171], v[202:205], v[86:89]
	v_mfma_f32_16x16x32_bf16 v[82:85], v[176:179], v[202:205], v[82:85]
	v_mfma_f32_16x16x32_bf16 v[70:73], v[168:171], v[210:213], v[70:73]
	v_mfma_f32_16x16x32_bf16 v[66:69], v[176:179], v[210:213], v[66:69]
	s_setprio 0
	s_barrier
	s_add_i32 s17, s20, s52
	v_lshl_add_u64 v[214:215], s[18:19], 0, v[132:133]
	s_mov_b32 m0, s17
	ds_read_b128 v[182:185], v159 offset:16384
	ds_read_b128 v[186:189], v159 offset:17408
	ds_read_b128 v[190:193], v159 offset:18432
	ds_read_b128 v[194:197], v159 offset:19456
	ds_read_b128 v[198:201], v159 offset:20480
	ds_read_b128 v[202:205], v159 offset:21504
	ds_read_b128 v[206:209], v159 offset:22528
	ds_read_b128 v[210:213], v159 offset:23552
	global_load_lds_dwordx4 v[214:215], off
	s_add_i32 m0, s17, 0x2000
	v_lshl_add_u64 v[216:217], s[18:19], 0, v[136:137]
	s_add_u32 s18, s18, s50
	s_addc_u32 s19, s19, 0
	s_add_i32 s15, s15, s52
	global_load_lds_dwordx4 v[216:217], off
	v_lshl_add_u64 v[218:219], s[18:19], 0, v[132:133]
	s_mov_b32 m0, s15
	v_lshl_add_u64 v[220:221], s[18:19], 0, v[136:137]
	global_load_lds_dwordx4 v[218:219], off
	s_add_i32 m0, s15, 0x2000
	v_lshl_add_u64 v[222:223], s[40:41], 0, v[130:131]
	global_load_lds_dwordx4 v[220:221], off
	s_mov_b32 m0, s53
	v_lshl_add_u64 v[224:225], s[40:41], 0, v[134:135]
	global_load_lds_dwordx4 v[222:223], off
	s_mov_b32 m0, s98
	s_nop 0
	global_load_lds_dwordx4 v[224:225], off
	s_waitcnt vmcnt(8)
	s_waitcnt lgkmcnt(0)
	s_barrier
; #define PG8_STAGE(bufoff, gbase, voff) do { _Pragma("unroll") for (int _i = 0; _i < 2; ++_i) \
;         __builtin_amdgcn_global_load_lds((const unsigned*)((const char*)(gbase) + (voff)[_i]), (LAS unsigned*)(lds + (bufoff) + ldsw + _i * 8192), 16, 0, 0); } while (0)
; #define PG8_LDA(dst, b, h) do { _Pragma("unroll") for (int m = 0; m < 4; ++m) _Pragma("unroll") for (int k = 0; k < 2; ++k) dst[m][k] = *(const LAS bf16x8*)(lds + PG8_SA(b, h) + aoff + m * 2048 + k * 1024); } while (0)
; #define PG8_LDB(dst, b, h) do { _Pragma("unroll") for (int n = 0; n < 2; ++n) _Pragma("unroll") for (int k = 0; k < 2; ++k) dst[n][k] = *(const LAS bf16x8*)(lds + PG8_SB(b, h) + boff + n * 2048 + k * 1024); } while (0)
; #define PG8_MMA(ai, bj, At, Bt) do { __builtin_amdgcn_s_setprio(1); _Pragma("unroll") for (int m = 0; m < 4; ++m) _Pragma("unroll") for (int n = 0; n < 2; ++n) _Pragma("unroll") for (int k = 0; k < 2; ++k) \
;         acc[ai][bj][m][n] = __builtin_amdgcn_mfma_f32_16x16x32_bf16(Bt[n][k], At[m][k], acc[ai][bj][m][n], 0, 0, 0); __builtin_amdgcn_s_setprio(0); } while (0)
; #define PG8_WAIT_V(n) asm volatile("s_waitcnt vmcnt(" #n ")" ::: "memory")
; #define PG8_WAIT_L(n) asm volatile("s_waitcnt lgkmcnt(" #n ")" ::: "memory")
; #define PG8_BAR __builtin_amdgcn_s_barrier()
; #define PG8_SCHED __builtin_amdgcn_sched_barrier(0)
; template <class Epi>
; __device__ __forceinline__ void gemm_phase(LAS unsigned char* lds, const Gemm g, const StaticOrder& S, const Epi& E) {
;     ...
;             PG8_WAIT_V(8); PG8_WAIT_L(0); PG8_BAR; PG8_MMA(1, 0, At, B0); PG8_MMA(1, 1, At, B1); PG8_BAR; PG8_SCHED;
;             PG8_LDB(B0, 1, 0); PG8_LDB(B1, 1, 1); PG8_SCHED; PG8_LDA(At, 1, 0); PG8_STAGE(PG8_SA(0, 1), a2 + hstepA, voffA);
;             PG8_WAIT_V(8); PG8_WAIT_L(0); PG8_BAR; PG8_MMA(0, 0, At, B0); PG8_MMA(0, 1, At, B1); PG8_BAR; PG8_SCHED;
	s_setprio 1
	v_mfma_f32_16x16x32_bf16 v[62:65], v[142:145], v[182:185], v[62:65]
	v_mfma_f32_16x16x32_bf16 v[58:61], v[150:153], v[182:185], v[58:61]
	v_mfma_f32_16x16x32_bf16 v[46:49], v[142:145], v[190:193], v[46:49]
	v_mfma_f32_16x16x32_bf16 v[42:45], v[150:153], v[190:193], v[42:45]
	v_mfma_f32_16x16x32_bf16 v[30:33], v[142:145], v[198:201], v[30:33]
	v_mfma_f32_16x16x32_bf16 v[26:29], v[150:153], v[198:201], v[26:29]
	v_mfma_f32_16x16x32_bf16 v[14:17], v[142:145], v[206:209], v[14:17]
	v_mfma_f32_16x16x32_bf16 v[10:13], v[150:153], v[206:209], v[10:13]
	v_mfma_f32_16x16x32_bf16 v[62:65], v[146:149], v[186:189], v[62:65]
	v_mfma_f32_16x16x32_bf16 v[58:61], v[160:163], v[186:189], v[58:61]
	v_mfma_f32_16x16x32_bf16 v[46:49], v[146:149], v[194:197], v[46:49]
	v_mfma_f32_16x16x32_bf16 v[42:45], v[160:163], v[194:197], v[42:45]
	v_mfma_f32_16x16x32_bf16 v[30:33], v[146:149], v[202:205], v[30:33]
	v_mfma_f32_16x16x32_bf16 v[26:29], v[160:163], v[202:205], v[26:29]
	v_mfma_f32_16x16x32_bf16 v[14:17], v[146:149], v[210:213], v[14:17]
	v_mfma_f32_16x16x32_bf16 v[10:13], v[160:163], v[210:213], v[10:13]
	s_setprio 0
	s_setprio 1
	v_mfma_f32_16x16x32_bf16 v[54:57], v[164:167], v[182:185], v[54:57]
	v_mfma_f32_16x16x32_bf16 v[50:53], v[172:175], v[182:185], v[50:53]
	v_mfma_f32_16x16x32_bf16 v[38:41], v[164:167], v[190:193], v[38:41]
	v_mfma_f32_16x16x32_bf16 v[34:37], v[172:175], v[190:193], v[34:37]
	v_mfma_f32_16x16x32_bf16 v[22:25], v[164:167], v[198:201], v[22:25]
	v_mfma_f32_16x16x32_bf16 v[18:21], v[172:175], v[198:201], v[18:21]
	v_mfma_f32_16x16x32_bf16 v[6:9], v[164:167], v[206:209], v[6:9]
	v_mfma_f32_16x16x32_bf16 v[2:5], v[172:175], v[206:209], v[2:5]
	v_mfma_f32_16x16x32_bf16 v[54:57], v[168:171], v[186:189], v[54:57]
	v_mfma_f32_16x16x32_bf16 v[50:53], v[176:179], v[186:189], v[50:53]
	v_mfma_f32_16x16x32_bf16 v[38:41], v[168:171], v[194:197], v[38:41]
	v_mfma_f32_16x16x32_bf16 v[34:37], v[176:179], v[194:197], v[34:37]
	v_mfma_f32_16x16x32_bf16 v[22:25], v[168:171], v[202:205], v[22:25]
	v_mfma_f32_16x16x32_bf16 v[18:21], v[176:179], v[202:205], v[18:21]
	v_mfma_f32_16x16x32_bf16 v[6:9], v[168:171], v[210:213], v[6:9]
	v_mfma_f32_16x16x32_bf16 v[2:5], v[176:179], v[210:213], v[2:5]
	s_setprio 0
	s_barrier
	s_add_i32 s15, 0, 0x18000
	v_add_u32_e32 v0, s15, v157
	s_add_i32 s17, 0, 0x1c000
	ds_read_b128 v[142:145], v0
	ds_read_b128 v[146:149], v0 offset:1024
	ds_read_b128 v[150:153], v0 offset:2048
	ds_read_b128 v[160:163], v0 offset:3072
	v_add_u32_e32 v0, s17, v157
	ds_read_b128 v[164:167], v0
	ds_read_b128 v[168:171], v0 offset:1024
	ds_read_b128 v[172:175], v0 offset:2048
	ds_read_b128 v[176:179], v0 offset:3072
	s_add_u32 s18, s40, 0x90000
	s_addc_u32 s19, s41, 0
	s_mov_b32 m0, s99
	v_lshl_add_u64 v[226:227], s[18:19], 0, v[130:131]
	ds_read_b128 v[182:185], v159 offset:32768
	ds_read_b128 v[186:189], v159 offset:33792
	ds_read_b128 v[190:193], v159 offset:34816
	ds_read_b128 v[194:197], v159 offset:35840
	ds_read_b128 v[198:201], v159 offset:36864
	ds_read_b128 v[202:205], v159 offset:37888
	ds_read_b128 v[206:209], v159 offset:38912
	ds_read_b128 v[210:213], v159 offset:39936
	global_load_lds_dwordx4 v[226:227], off
	v_lshl_add_u64 v[226:227], s[18:19], 0, v[134:135]
	s_mov_b32 m0, s56
	s_nop 0
	global_load_lds_dwordx4 v[226:227], off
	s_waitcnt vmcnt(8)
	s_waitcnt lgkmcnt(0)
	s_barrier
	s_setprio 1
	v_mfma_f32_16x16x32_bf16 v[126:129], v[142:145], v[182:185], v[126:129]
	v_mfma_f32_16x16x32_bf16 v[122:125], v[150:153], v[182:185], v[122:125]
	v_mfma_f32_16x16x32_bf16 v[110:113], v[142:145], v[190:193], v[110:113]
	v_mfma_f32_16x16x32_bf16 v[106:109], v[150:153], v[190:193], v[106:109]
	v_mfma_f32_16x16x32_bf16 v[94:97], v[142:145], v[198:201], v[94:97]
	v_mfma_f32_16x16x32_bf16 v[90:93], v[150:153], v[198:201], v[90:93]
	v_mfma_f32_16x16x32_bf16 v[78:81], v[142:145], v[206:209], v[78:81]
	v_mfma_f32_16x16x32_bf16 v[74:77], v[150:153], v[206:209], v[74:77]
	v_mfma_f32_16x16x32_bf16 v[126:129], v[146:149], v[186:189], v[126:129]
	v_mfma_f32_16x16x32_bf16 v[122:125], v[160:163], v[186:189], v[122:125]
	v_mfma_f32_16x16x32_bf16 v[110:113], v[146:149], v[194:197], v[110:113]
	v_mfma_f32_16x16x32_bf16 v[106:109], v[160:163], v[194:197], v[106:109]
	v_mfma_f32_16x16x32_bf16 v[94:97], v[146:149], v[202:205], v[94:97]
	v_mfma_f32_16x16x32_bf16 v[90:93], v[160:163], v[202:205], v[90:93]
	v_mfma_f32_16x16x32_bf16 v[78:81], v[146:149], v[210:213], v[78:81]
	v_mfma_f32_16x16x32_bf16 v[74:77], v[160:163], v[210:213], v[74:77]
	s_setprio 0
	s_setprio 1
	v_mfma_f32_16x16x32_bf16 v[118:121], v[164:167], v[182:185], v[118:121]
	v_mfma_f32_16x16x32_bf16 v[114:117], v[172:175], v[182:185], v[114:117]
	v_mfma_f32_16x16x32_bf16 v[102:105], v[164:167], v[190:193], v[102:105]
	v_mfma_f32_16x16x32_bf16 v[98:101], v[172:175], v[190:193], v[98:101]
	v_mfma_f32_16x16x32_bf16 v[86:89], v[164:167], v[198:201], v[86:89]
	v_mfma_f32_16x16x32_bf16 v[82:85], v[172:175], v[198:201], v[82:85]
	v_mfma_f32_16x16x32_bf16 v[70:73], v[164:167], v[206:209], v[70:73]
	v_mfma_f32_16x16x32_bf16 v[66:69], v[172:175], v[206:209], v[66:69]
	v_mfma_f32_16x16x32_bf16 v[118:121], v[168:171], v[186:189], v[118:121]
	v_mfma_f32_16x16x32_bf16 v[114:117], v[176:179], v[186:189], v[114:117]
	v_mfma_f32_16x16x32_bf16 v[102:105], v[168:171], v[194:197], v[102:105]
	v_mfma_f32_16x16x32_bf16 v[98:101], v[176:179], v[194:197], v[98:101]
	v_mfma_f32_16x16x32_bf16 v[86:89], v[168:171], v[202:205], v[86:89]
	v_mfma_f32_16x16x32_bf16 v[82:85], v[176:179], v[202:205], v[82:85]
	v_mfma_f32_16x16x32_bf16 v[70:73], v[168:171], v[210:213], v[70:73]
	v_mfma_f32_16x16x32_bf16 v[66:69], v[176:179], v[210:213], v[66:69]
	s_setprio 0
	s_barrier
; #define PG8_STAGE(bufoff, gbase, voff) do { _Pragma("unroll") for (int _i = 0; _i < 2; ++_i) \
;         __builtin_amdgcn_global_load_lds((const unsigned*)((const char*)(gbase) + (voff)[_i]), (LAS unsigned*)(lds + (bufoff) + ldsw + _i * 8192), 16, 0, 0); } while (0)
; #define PG8_LDA(dst, b, h) do { _Pragma("unroll") for (int m = 0; m < 4; ++m) _Pragma("unroll") for (int k = 0; k < 2; ++k) dst[m][k] = *(const LAS bf16x8*)(lds + PG8_SA(b, h) + aoff + m * 2048 + k * 1024); } while (0)
; #define PG8_MMA(ai, bj, At, Bt) do { __builtin_amdgcn_s_setprio(1); _Pragma("unroll") for (int m = 0; m < 4; ++m) _Pragma("unroll") for (int n = 0; n < 2; ++n) _Pragma("unroll") for (int k = 0; k < 2; ++k) \
;         acc[ai][bj][m][n] = __builtin_amdgcn_mfma_f32_16x16x32_bf16(Bt[n][k], At[m][k], acc[ai][bj][m][n], 0, 0, 0); __builtin_amdgcn_s_setprio(0); } while (0)
; #define PG8_WAIT_V(n) asm volatile("s_waitcnt vmcnt(" #n ")" ::: "memory")
; #define PG8_WAIT_L(n) asm volatile("s_waitcnt lgkmcnt(" #n ")" ::: "memory")
; #define PG8_BAR __builtin_amdgcn_s_barrier()
; #define PG8_SCHED __builtin_amdgcn_sched_barrier(0)
; template <class Epi>
; __device__ __forceinline__ void gemm_phase(LAS unsigned char* lds, const Gemm g, const StaticOrder& S, const Epi& E) {
;     ...
;             PG8_LDA(At, 1, 1); PG8_STAGE(PG8_SB(1, 0), b3, voffB); PG8_STAGE(PG8_SB(1, 1), b3 + hstepB, voffB); PG8_STAGE(PG8_SA(1, 0), a3, voffA);
;             PG8_WAIT_V(8); PG8_WAIT_L(0); PG8_BAR; PG8_MMA(1, 0, At, B0); PG8_MMA(1, 1, At, B1); PG8_BAR; PG8_SCHED;
;         }
;         if (wr == 0) PG8_BAR;
	s_add_i32 s15, s15, s52
	v_lshl_add_u64 v[214:215], v[214:215], 0, s[34:35]
	s_mov_b32 m0, s15
	ds_read_b128 v[182:185], v159 offset:49152
	ds_read_b128 v[186:189], v159 offset:50176
	ds_read_b128 v[190:193], v159 offset:51200
	ds_read_b128 v[194:197], v159 offset:52224
	ds_read_b128 v[198:201], v159 offset:53248
	ds_read_b128 v[202:205], v159 offset:54272
	ds_read_b128 v[206:209], v159 offset:55296
	ds_read_b128 v[210:213], v159 offset:56320
	global_load_lds_dwordx4 v[214:215], off
	v_lshl_add_u64 v[214:215], v[216:217], 0, s[34:35]
	s_add_i32 m0, s15, 0x2000
	s_add_i32 s15, s17, s52
	global_load_lds_dwordx4 v[214:215], off
	v_lshl_add_u64 v[214:215], v[218:219], 0, s[34:35]
	s_mov_b32 m0, s15
	s_nop 0
	global_load_lds_dwordx4 v[214:215], off
	v_lshl_add_u64 v[214:215], v[220:221], 0, s[34:35]
	s_add_i32 m0, s15, 0x2000
	s_nop 0
	global_load_lds_dwordx4 v[214:215], off
	v_lshl_add_u64 v[214:215], v[222:223], 0, s[34:35]
	s_mov_b32 m0, s61
	s_nop 0
	global_load_lds_dwordx4 v[214:215], off
	v_lshl_add_u64 v[214:215], v[224:225], 0, s[34:35]
	s_mov_b32 m0, s80
	s_nop 0
	global_load_lds_dwordx4 v[214:215], off
	s_waitcnt vmcnt(8)
	s_waitcnt lgkmcnt(0)
	s_barrier
	s_setprio 1
	v_mfma_f32_16x16x32_bf16 v[62:65], v[142:145], v[182:185], v[62:65]
	v_mfma_f32_16x16x32_bf16 v[58:61], v[150:153], v[182:185], v[58:61]
	v_mfma_f32_16x16x32_bf16 v[46:49], v[142:145], v[190:193], v[46:49]
	v_mfma_f32_16x16x32_bf16 v[42:45], v[150:153], v[190:193], v[42:45]
	v_mfma_f32_16x16x32_bf16 v[30:33], v[142:145], v[198:201], v[30:33]
	v_mfma_f32_16x16x32_bf16 v[26:29], v[150:153], v[198:201], v[26:29]
	v_mfma_f32_16x16x32_bf16 v[14:17], v[142:145], v[206:209], v[14:17]
	v_mfma_f32_16x16x32_bf16 v[10:13], v[150:153], v[206:209], v[10:13]
	v_mfma_f32_16x16x32_bf16 v[62:65], v[146:149], v[186:189], v[62:65]
	v_mfma_f32_16x16x32_bf16 v[58:61], v[160:163], v[186:189], v[58:61]
	v_mfma_f32_16x16x32_bf16 v[46:49], v[146:149], v[194:197], v[46:49]
	v_mfma_f32_16x16x32_bf16 v[42:45], v[160:163], v[194:197], v[42:45]
	v_mfma_f32_16x16x32_bf16 v[30:33], v[146:149], v[202:205], v[30:33]
	v_mfma_f32_16x16x32_bf16 v[26:29], v[160:163], v[202:205], v[26:29]
	v_mfma_f32_16x16x32_bf16 v[14:17], v[146:149], v[210:213], v[14:17]
	v_mfma_f32_16x16x32_bf16 v[10:13], v[160:163], v[210:213], v[10:13]
	s_setprio 0
	s_setprio 1
	v_mfma_f32_16x16x32_bf16 v[54:57], v[164:167], v[182:185], v[54:57]
	v_mfma_f32_16x16x32_bf16 v[50:53], v[172:175], v[182:185], v[50:53]
	v_mfma_f32_16x16x32_bf16 v[38:41], v[164:167], v[190:193], v[38:41]
	v_mfma_f32_16x16x32_bf16 v[34:37], v[172:175], v[190:193], v[34:37]
	v_mfma_f32_16x16x32_bf16 v[22:25], v[164:167], v[198:201], v[22:25]
	v_mfma_f32_16x16x32_bf16 v[18:21], v[172:175], v[198:201], v[18:21]
	v_mfma_f32_16x16x32_bf16 v[6:9], v[164:167], v[206:209], v[6:9]
	v_mfma_f32_16x16x32_bf16 v[2:5], v[172:175], v[206:209], v[2:5]
	v_mfma_f32_16x16x32_bf16 v[54:57], v[168:171], v[186:189], v[54:57]
	v_mfma_f32_16x16x32_bf16 v[50:53], v[176:179], v[186:189], v[50:53]
	v_mfma_f32_16x16x32_bf16 v[38:41], v[168:171], v[194:197], v[38:41]
	v_mfma_f32_16x16x32_bf16 v[34:37], v[176:179], v[194:197], v[34:37]
	v_mfma_f32_16x16x32_bf16 v[22:25], v[168:171], v[202:205], v[22:25]
	v_mfma_f32_16x16x32_bf16 v[18:21], v[176:179], v[202:205], v[18:21]
	v_mfma_f32_16x16x32_bf16 v[6:9], v[168:171], v[210:213], v[6:9]
	v_mfma_f32_16x16x32_bf16 v[2:5], v[176:179], v[210:213], v[2:5]
	s_setprio 0
	s_barrier
	s_add_u32 s13, s13, 0x100
	s_addc_u32 s14, s14, 0
	s_add_u32 s0, s0, 0x100
	s_addc_u32 s1, s1, 0
	s_cmp_ge_u32 s16, s31
	s_mov_b32 s15, s16
	s_cbranch_scc0 .LBB0_187
	s_and_b64 vcc, exec, s[88:89]
	s_cbranch_vccz .LBB0_190
	s_barrier

; #define PG8_STAGE(bufoff, gbase, voff) do { _Pragma("unroll") for (int _i = 0; _i < 2; ++_i) \
;         __builtin_amdgcn_global_load_lds((const unsigned*)((const char*)(gbase) + (voff)[_i]), (LAS unsigned*)(lds + (bufoff) + ldsw + _i * 8192), 16, 0, 0); } while (0)
; #define PG8_LDA(dst, b, h) do { _Pragma("unroll") for (int m = 0; m < 4; ++m) _Pragma("unroll") for (int k = 0; k < 2; ++k) dst[m][k] = *(const LAS bf16x8*)(lds + PG8_SA(b, h) + aoff + m * 2048 + k * 1024); } while (0)
; #define PG8_LDB(dst, b, h) do { _Pragma("unroll") for (int n = 0; n < 2; ++n) _Pragma("unroll") for (int k = 0; k < 2; ++k) dst[n][k] = *(const LAS bf16x8*)(lds + PG8_SB(b, h) + boff + n * 2048 + k * 1024); } while (0)
; #define PG8_MMA(ai, bj, At, Bt) do { __builtin_amdgcn_s_setprio(1); _Pragma("unroll") for (int m = 0; m < 4; ++m) _Pragma("unroll") for (int n = 0; n < 2; ++n) _Pragma("unroll") for (int k = 0; k < 2; ++k) \
;         acc[ai][bj][m][n] = __builtin_amdgcn_mfma_f32_16x16x32_bf16(Bt[n][k], At[m][k], acc[ai][bj][m][n], 0, 0, 0); __builtin_amdgcn_s_setprio(0); } while (0)
; #define PG8_WAIT_V(n) asm volatile("s_waitcnt vmcnt(" #n ")" ::: "memory")
; #define PG8_WAIT_L(n) asm volatile("s_waitcnt lgkmcnt(" #n ")" ::: "memory")
; #define PG8_BAR __builtin_amdgcn_s_barrier()
; #define PG8_SCHED __builtin_amdgcn_sched_barrier(0)
; template <class Epi>
; __device__ __forceinline__ void gemm_phase(LAS unsigned char* lds, const Gemm g, const StaticOrder& S, const Epi& E) {
;     ...
;             PG8_LDB(B0, 0, 0); PG8_LDB(B1, 0, 1); PG8_SCHED; PG8_LDA(At, 0, 0); PG8_STAGE(PG8_SA(1, 1), a1 + hstepA, voffA);
;             PG8_WAIT_V(8); PG8_WAIT_L(0); PG8_BAR; PG8_MMA(0, 0, At, B0); PG8_MMA(0, 1, At, B1); PG8_BAR; PG8_SCHED;
;             PG8_LDA(At, 0, 1); PG8_STAGE(PG8_SB(0, 0), b2, voffB); PG8_STAGE(PG8_SB(0, 1), b2 + hstepB, voffB); PG8_STAGE(PG8_SA(0, 0), a2, voffA);
;             PG8_WAIT_V(8); PG8_WAIT_L(0); PG8_BAR; PG8_MMA(1, 0, At, B0); PG8_MMA(1, 1, At, B1); PG8_BAR; PG8_SCHED;
.LBB0_308:
	s_add_i32 s50, s4, 2
	s_add_u32 s51, s0, 0x80
	s_addc_u32 s5, s1, 0
	s_add_i32 s61, 0, 0x10000
	s_cmp_eq_u32 s27, s4
	s_cselect_b32 s5, s95, s5
	s_cselect_b32 s4, s94, s51
	s_cselect_b32 s53, s97, s49
	s_cselect_b32 s52, s96, s48
	s_add_i32 s51, 0, 0x14000
	v_add_u32_e32 v142, s61, v237
	v_add_u32_e32 v158, s51, v237
	ds_read_b128 v[130:133], v142
	ds_read_b128 v[134:137], v142 offset:1024
	ds_read_b128 v[138:141], v142 offset:2048
	ds_read_b128 v[142:145], v142 offset:3072
	ds_read_b128 v[146:149], v158
	ds_read_b128 v[150:153], v158 offset:1024
	ds_read_b128 v[154:157], v158 offset:2048
	ds_read_b128 v[158:161], v158 offset:3072
	v_lshl_add_u64 v[178:179], s[0:1], 0, v[190:191]
	s_add_i32 m0, s19, 0xc000
	ds_read_b128 v[162:165], v243
	ds_read_b128 v[166:169], v243 offset:1024
	ds_read_b128 v[170:173], v243 offset:2048
	ds_read_b128 v[174:177], v243 offset:3072
	ds_read_b128 v[192:195], v243 offset:4096
	ds_read_b128 v[196:199], v243 offset:5120
	ds_read_b128 v[200:203], v243 offset:6144
	ds_read_b128 v[204:207], v243 offset:7168
	global_load_lds_dwordx4 v[178:179], off
	v_lshl_add_u64 v[178:179], s[0:1], 0, v[188:189]
	s_add_i32 m0, s19, 0xe000
	s_nop 0
	global_load_lds_dwordx4 v[178:179], off
	s_waitcnt vmcnt(8)
	s_waitcnt lgkmcnt(0)
	s_barrier
	s_setprio 1
	v_mfma_f32_16x16x32_bf16 v[126:129], v[130:133], v[162:165], v[126:129]
	v_mfma_f32_16x16x32_bf16 v[122:125], v[138:141], v[162:165], v[122:125]
	v_mfma_f32_16x16x32_bf16 v[118:121], v[130:133], v[170:173], v[118:121]
	v_mfma_f32_16x16x32_bf16 v[114:117], v[138:141], v[170:173], v[114:117]
	v_mfma_f32_16x16x32_bf16 v[110:113], v[130:133], v[192:195], v[110:113]
	v_mfma_f32_16x16x32_bf16 v[106:109], v[138:141], v[192:195], v[106:109]
	v_mfma_f32_16x16x32_bf16 v[102:105], v[130:133], v[200:203], v[102:105]
	v_mfma_f32_16x16x32_bf16 v[98:101], v[138:141], v[200:203], v[98:101]
	v_mfma_f32_16x16x32_bf16 v[126:129], v[134:137], v[166:169], v[126:129]
	v_mfma_f32_16x16x32_bf16 v[122:125], v[142:145], v[166:169], v[122:125]
	v_mfma_f32_16x16x32_bf16 v[118:121], v[134:137], v[174:177], v[118:121]
	v_mfma_f32_16x16x32_bf16 v[114:117], v[142:145], v[174:177], v[114:117]
	v_mfma_f32_16x16x32_bf16 v[110:113], v[134:137], v[196:199], v[110:113]
	v_mfma_f32_16x16x32_bf16 v[106:109], v[142:145], v[196:199], v[106:109]
	v_mfma_f32_16x16x32_bf16 v[102:105], v[134:137], v[204:207], v[102:105]
	v_mfma_f32_16x16x32_bf16 v[98:101], v[142:145], v[204:207], v[98:101]
	s_setprio 0
	s_setprio 1
	v_mfma_f32_16x16x32_bf16 v[94:97], v[146:149], v[162:165], v[94:97]
	v_mfma_f32_16x16x32_bf16 v[90:93], v[154:157], v[162:165], v[90:93]
	v_mfma_f32_16x16x32_bf16 v[86:89], v[146:149], v[170:173], v[86:89]
	v_mfma_f32_16x16x32_bf16 v[82:85], v[154:157], v[170:173], v[82:85]
	v_mfma_f32_16x16x32_bf16 v[78:81], v[146:149], v[192:195], v[78:81]
	v_mfma_f32_16x16x32_bf16 v[74:77], v[154:157], v[192:195], v[74:77]
	v_mfma_f32_16x16x32_bf16 v[70:73], v[146:149], v[200:203], v[70:73]
	v_mfma_f32_16x16x32_bf16 v[66:69], v[154:157], v[200:203], v[66:69]
	v_mfma_f32_16x16x32_bf16 v[94:97], v[150:153], v[166:169], v[94:97]
	v_mfma_f32_16x16x32_bf16 v[90:93], v[158:161], v[166:169], v[90:93]
	v_mfma_f32_16x16x32_bf16 v[86:89], v[150:153], v[174:177], v[86:89]
	v_mfma_f32_16x16x32_bf16 v[82:85], v[158:161], v[174:177], v[82:85]
	v_mfma_f32_16x16x32_bf16 v[78:81], v[150:153], v[196:199], v[78:81]
	v_mfma_f32_16x16x32_bf16 v[74:77], v[158:161], v[196:199], v[74:77]
	v_mfma_f32_16x16x32_bf16 v[70:73], v[150:153], v[204:207], v[70:73]
	v_mfma_f32_16x16x32_bf16 v[66:69], v[158:161], v[204:207], v[66:69]
	s_setprio 0
	s_barrier
	s_add_i32 s61, s61, s16
	v_lshl_add_u64 v[178:179], s[52:53], 0, v[0:1]
	s_mov_b32 m0, s61
	ds_read_b128 v[162:165], v243 offset:16384
	ds_read_b128 v[166:169], v243 offset:17408
	ds_read_b128 v[170:173], v243 offset:18432
	ds_read_b128 v[174:177], v243 offset:19456
	ds_read_b128 v[192:195], v243 offset:20480
	ds_read_b128 v[196:199], v243 offset:21504
	ds_read_b128 v[200:203], v243 offset:22528
	ds_read_b128 v[204:207], v243 offset:23552
	global_load_lds_dwordx4 v[178:179], off
	s_add_i32 m0, s61, 0x2000
	v_lshl_add_u64 v[208:209], s[52:53], 0, v[186:187]
	s_add_u32 s52, s52, s46
	s_addc_u32 s53, s53, 0
	s_add_i32 s51, s51, s16
	global_load_lds_dwordx4 v[208:209], off
	v_lshl_add_u64 v[210:211], s[52:53], 0, v[0:1]
	s_mov_b32 m0, s51
	v_lshl_add_u64 v[212:213], s[52:53], 0, v[186:187]
	global_load_lds_dwordx4 v[210:211], off
	s_add_i32 m0, s51, 0x2000
	v_lshl_add_u64 v[214:215], s[4:5], 0, v[182:183]
	global_load_lds_dwordx4 v[212:213], off
	s_mov_b32 m0, s19
	v_lshl_add_u64 v[216:217], s[4:5], 0, v[184:185]
	global_load_lds_dwordx4 v[214:215], off
	s_mov_b32 m0, s20
	s_nop 0
	global_load_lds_dwordx4 v[216:217], off
	s_waitcnt vmcnt(8)
	s_waitcnt lgkmcnt(0)
	s_barrier
; #define PG8_STAGE(bufoff, gbase, voff) do { _Pragma("unroll") for (int _i = 0; _i < 2; ++_i) \
;         __builtin_amdgcn_global_load_lds((const unsigned*)((const char*)(gbase) + (voff)[_i]), (LAS unsigned*)(lds + (bufoff) + ldsw + _i * 8192), 16, 0, 0); } while (0)
; #define PG8_LDA(dst, b, h) do { _Pragma("unroll") for (int m = 0; m < 4; ++m) _Pragma("unroll") for (int k = 0; k < 2; ++k) dst[m][k] = *(const LAS bf16x8*)(lds + PG8_SA(b, h) + aoff + m * 2048 + k * 1024); } while (0)
; #define PG8_LDB(dst, b, h) do { _Pragma("unroll") for (int n = 0; n < 2; ++n) _Pragma("unroll") for (int k = 0; k < 2; ++k) dst[n][k] = *(const LAS bf16x8*)(lds + PG8_SB(b, h) + boff + n * 2048 + k * 1024); } while (0)
; #define PG8_MMA(ai, bj, At, Bt) do { __builtin_amdgcn_s_setprio(1); _Pragma("unroll") for (int m = 0; m < 4; ++m) _Pragma("unroll") for (int n = 0; n < 2; ++n) _Pragma("unroll") for (int k = 0; k < 2; ++k) \
;         acc[ai][bj][m][n] = __builtin_amdgcn_mfma_f32_16x16x32_bf16(Bt[n][k], At[m][k], acc[ai][bj][m][n], 0, 0, 0); __builtin_amdgcn_s_setprio(0); } while (0)
; #define PG8_WAIT_V(n) asm volatile("s_waitcnt vmcnt(" #n ")" ::: "memory")
; #define PG8_WAIT_L(n) asm volatile("s_waitcnt lgkmcnt(" #n ")" ::: "memory")
; #define PG8_BAR __builtin_amdgcn_s_barrier()
; #define PG8_SCHED __builtin_amdgcn_sched_barrier(0)
; template <class Epi>
; __device__ __forceinline__ void gemm_phase(LAS unsigned char* lds, const Gemm g, const StaticOrder& S, const Epi& E) {
;     ...
;             PG8_WAIT_V(8); PG8_WAIT_L(0); PG8_BAR; PG8_MMA(1, 0, At, B0); PG8_MMA(1, 1, At, B1); PG8_BAR; PG8_SCHED;
;             PG8_LDB(B0, 1, 0); PG8_LDB(B1, 1, 1); PG8_SCHED; PG8_LDA(At, 1, 0); PG8_STAGE(PG8_SA(0, 1), a2 + hstepA, voffA);
;             PG8_WAIT_V(8); PG8_WAIT_L(0); PG8_BAR; PG8_MMA(0, 0, At, B0); PG8_MMA(0, 1, At, B1); PG8_BAR; PG8_SCHED;
	s_setprio 1
	v_mfma_f32_16x16x32_bf16 v[62:65], v[130:133], v[162:165], v[62:65]
	v_mfma_f32_16x16x32_bf16 v[58:61], v[138:141], v[162:165], v[58:61]
	v_mfma_f32_16x16x32_bf16 v[54:57], v[130:133], v[170:173], v[54:57]
	v_mfma_f32_16x16x32_bf16 v[50:53], v[138:141], v[170:173], v[50:53]
	v_mfma_f32_16x16x32_bf16 v[46:49], v[130:133], v[192:195], v[46:49]
	v_mfma_f32_16x16x32_bf16 v[42:45], v[138:141], v[192:195], v[42:45]
	v_mfma_f32_16x16x32_bf16 v[38:41], v[130:133], v[200:203], v[38:41]
	v_mfma_f32_16x16x32_bf16 v[34:37], v[138:141], v[200:203], v[34:37]
	v_mfma_f32_16x16x32_bf16 v[62:65], v[134:137], v[166:169], v[62:65]
	v_mfma_f32_16x16x32_bf16 v[58:61], v[142:145], v[166:169], v[58:61]
	v_mfma_f32_16x16x32_bf16 v[54:57], v[134:137], v[174:177], v[54:57]
	v_mfma_f32_16x16x32_bf16 v[50:53], v[142:145], v[174:177], v[50:53]
	v_mfma_f32_16x16x32_bf16 v[46:49], v[134:137], v[196:199], v[46:49]
	v_mfma_f32_16x16x32_bf16 v[42:45], v[142:145], v[196:199], v[42:45]
	v_mfma_f32_16x16x32_bf16 v[38:41], v[134:137], v[204:207], v[38:41]
	v_mfma_f32_16x16x32_bf16 v[34:37], v[142:145], v[204:207], v[34:37]
	s_setprio 0
	s_setprio 1
	v_mfma_f32_16x16x32_bf16 v[30:33], v[146:149], v[162:165], v[30:33]
	v_mfma_f32_16x16x32_bf16 v[26:29], v[154:157], v[162:165], v[26:29]
	v_mfma_f32_16x16x32_bf16 v[22:25], v[146:149], v[170:173], v[22:25]
	v_mfma_f32_16x16x32_bf16 v[18:21], v[154:157], v[170:173], v[18:21]
	v_mfma_f32_16x16x32_bf16 v[14:17], v[146:149], v[192:195], v[14:17]
	v_mfma_f32_16x16x32_bf16 v[10:13], v[154:157], v[192:195], v[10:13]
	v_mfma_f32_16x16x32_bf16 v[6:9], v[146:149], v[200:203], v[6:9]
	v_mfma_f32_16x16x32_bf16 v[2:5], v[154:157], v[200:203], v[2:5]
	v_mfma_f32_16x16x32_bf16 v[30:33], v[150:153], v[166:169], v[30:33]
	v_mfma_f32_16x16x32_bf16 v[26:29], v[158:161], v[166:169], v[26:29]
	v_mfma_f32_16x16x32_bf16 v[22:25], v[150:153], v[174:177], v[22:25]
	v_mfma_f32_16x16x32_bf16 v[18:21], v[158:161], v[174:177], v[18:21]
	v_mfma_f32_16x16x32_bf16 v[14:17], v[150:153], v[196:199], v[14:17]
	v_mfma_f32_16x16x32_bf16 v[10:13], v[158:161], v[196:199], v[10:13]
	v_mfma_f32_16x16x32_bf16 v[6:9], v[150:153], v[204:207], v[6:9]
	v_mfma_f32_16x16x32_bf16 v[2:5], v[158:161], v[204:207], v[2:5]
	s_setprio 0
	s_barrier
	s_add_i32 s51, 0, 0x18000
	s_add_i32 s52, 0, 0x1c000
	v_add_u32_e32 v142, s51, v237
	v_add_u32_e32 v158, s52, v237
	ds_read_b128 v[130:133], v142
	ds_read_b128 v[134:137], v142 offset:1024
	ds_read_b128 v[138:141], v142 offset:2048
	ds_read_b128 v[142:145], v142 offset:3072
	ds_read_b128 v[146:149], v158
	ds_read_b128 v[150:153], v158 offset:1024
	ds_read_b128 v[154:157], v158 offset:2048
	ds_read_b128 v[158:161], v158 offset:3072
	s_add_u32 s4, s4, s46
	s_addc_u32 s5, s5, 0
	s_mov_b32 m0, s21
	v_lshl_add_u64 v[218:219], s[4:5], 0, v[182:183]
	ds_read_b128 v[162:165], v243 offset:32768
	ds_read_b128 v[166:169], v243 offset:33792
	ds_read_b128 v[170:173], v243 offset:34816
	ds_read_b128 v[174:177], v243 offset:35840
	ds_read_b128 v[192:195], v243 offset:36864
	ds_read_b128 v[196:199], v243 offset:37888
	ds_read_b128 v[200:203], v243 offset:38912
	ds_read_b128 v[204:207], v243 offset:39936
	global_load_lds_dwordx4 v[218:219], off
	v_lshl_add_u64 v[218:219], s[4:5], 0, v[184:185]
	s_mov_b32 m0, s22
	s_nop 0
	global_load_lds_dwordx4 v[218:219], off
	s_waitcnt vmcnt(8)
	s_waitcnt lgkmcnt(0)
	s_barrier
	s_setprio 1
	v_mfma_f32_16x16x32_bf16 v[126:129], v[130:133], v[162:165], v[126:129]
	v_mfma_f32_16x16x32_bf16 v[122:125], v[138:141], v[162:165], v[122:125]
	v_mfma_f32_16x16x32_bf16 v[118:121], v[130:133], v[170:173], v[118:121]
	v_mfma_f32_16x16x32_bf16 v[114:117], v[138:141], v[170:173], v[114:117]
	v_mfma_f32_16x16x32_bf16 v[110:113], v[130:133], v[192:195], v[110:113]
	v_mfma_f32_16x16x32_bf16 v[106:109], v[138:141], v[192:195], v[106:109]
	v_mfma_f32_16x16x32_bf16 v[102:105], v[130:133], v[200:203], v[102:105]
	v_mfma_f32_16x16x32_bf16 v[98:101], v[138:141], v[200:203], v[98:101]
	v_mfma_f32_16x16x32_bf16 v[126:129], v[134:137], v[166:169], v[126:129]
	v_mfma_f32_16x16x32_bf16 v[122:125], v[142:145], v[166:169], v[122:125]
	v_mfma_f32_16x16x32_bf16 v[118:121], v[134:137], v[174:177], v[118:121]
	v_mfma_f32_16x16x32_bf16 v[114:117], v[142:145], v[174:177], v[114:117]
	v_mfma_f32_16x16x32_bf16 v[110:113], v[134:137], v[196:199], v[110:113]
	v_mfma_f32_16x16x32_bf16 v[106:109], v[142:145], v[196:199], v[106:109]
	v_mfma_f32_16x16x32_bf16 v[102:105], v[134:137], v[204:207], v[102:105]
	v_mfma_f32_16x16x32_bf16 v[98:101], v[142:145], v[204:207], v[98:101]
	s_setprio 0
	s_setprio 1
	v_mfma_f32_16x16x32_bf16 v[94:97], v[146:149], v[162:165], v[94:97]
	v_mfma_f32_16x16x32_bf16 v[90:93], v[154:157], v[162:165], v[90:93]
	v_mfma_f32_16x16x32_bf16 v[86:89], v[146:149], v[170:173], v[86:89]
	v_mfma_f32_16x16x32_bf16 v[82:85], v[154:157], v[170:173], v[82:85]
	v_mfma_f32_16x16x32_bf16 v[78:81], v[146:149], v[192:195], v[78:81]
	v_mfma_f32_16x16x32_bf16 v[74:77], v[154:157], v[192:195], v[74:77]
	v_mfma_f32_16x16x32_bf16 v[70:73], v[146:149], v[200:203], v[70:73]
	v_mfma_f32_16x16x32_bf16 v[66:69], v[154:157], v[200:203], v[66:69]
	v_mfma_f32_16x16x32_bf16 v[94:97], v[150:153], v[166:169], v[94:97]
	v_mfma_f32_16x16x32_bf16 v[90:93], v[158:161], v[166:169], v[90:93]
	v_mfma_f32_16x16x32_bf16 v[86:89], v[150:153], v[174:177], v[86:89]
	v_mfma_f32_16x16x32_bf16 v[82:85], v[158:161], v[174:177], v[82:85]
	v_mfma_f32_16x16x32_bf16 v[78:81], v[150:153], v[196:199], v[78:81]
	v_mfma_f32_16x16x32_bf16 v[74:77], v[158:161], v[196:199], v[74:77]
	v_mfma_f32_16x16x32_bf16 v[70:73], v[150:153], v[204:207], v[70:73]
	v_mfma_f32_16x16x32_bf16 v[66:69], v[158:161], v[204:207], v[66:69]
	s_setprio 0
	s_barrier
; #define PG8_STAGE(bufoff, gbase, voff) do { _Pragma("unroll") for (int _i = 0; _i < 2; ++_i) \
;         __builtin_amdgcn_global_load_lds((const unsigned*)((const char*)(gbase) + (voff)[_i]), (LAS unsigned*)(lds + (bufoff) + ldsw + _i * 8192), 16, 0, 0); } while (0)
; #define PG8_LDA(dst, b, h) do { _Pragma("unroll") for (int m = 0; m < 4; ++m) _Pragma("unroll") for (int k = 0; k < 2; ++k) dst[m][k] = *(const LAS bf16x8*)(lds + PG8_SA(b, h) + aoff + m * 2048 + k * 1024); } while (0)
; #define PG8_LDB(dst, b, h) do { _Pragma("unroll") for (int n = 0; n < 2; ++n) _Pragma("unroll") for (int k = 0; k < 2; ++k) dst[n][k] = *(const LAS bf16x8*)(lds + PG8_SB(b, h) + boff + n * 2048 + k * 1024); } while (0)
; template <class Epi>
; __device__ __forceinline__ void gemm_phase(LAS unsigned char* lds, const Gemm g, const StaticOrder& S, const Epi& E) {
;     ...
;         for (int t = 0; t < nt; t += 2) {
;             const bool last = (t == nt - 2);
;             if constexpr (Epi::PREFETCH) { if (t == 2) E.prefetch(cur, wr, wc, lane); }
;             const char* a1 = cA + (size_t)(t + 1) * kstep;
;             const char* a2 = last ? nA : cA + (size_t)(t + 2) * kstep; const char* b2 = last ? nB : cB + (size_t)(t + 2) * kstep;
;             const char* a3 = a2 + kstep; const char* b3 = b2 + kstep;
;             PG8_LDB(B0, 0, 0); PG8_LDB(B1, 0, 1); PG8_SCHED; PG8_LDA(At, 0, 0); PG8_STAGE(PG8_SA(1, 1), a1 + hstepA, voffA);
;             PG8_WAIT_V(8); PG8_WAIT_L(0); PG8_BAR; PG8_MMA(0, 0, At, B0); PG8_MMA(0, 1, At, B1); PG8_BAR; PG8_SCHED;
;             PG8_LDA(At, 0, 1); PG8_STAGE(PG8_SB(0, 0), b2, voffB); PG8_STAGE(PG8_SB(0, 1), b2 + hstepB, voffB); PG8_STAGE(PG8_SA(0, 0), a2, voffA);
;             PG8_WAIT_V(8); PG8_WAIT_L(0); PG8_BAR; PG8_MMA(1, 0, At, B0); PG8_MMA(1, 1, At, B1); PG8_BAR; PG8_SCHED;
;             PG8_LDB(B0, 1, 0); PG8_LDB(B1, 1, 1); PG8_SCHED; PG8_LDA(At, 1, 0); PG8_STAGE(PG8_SA(0, 1), a2 + hstepA, voffA);
;             PG8_WAIT_V(8); PG8_WAIT_L(0); PG8_BAR; PG8_MMA(0, 0, At, B0); PG8_MMA(0, 1, At, B1); PG8_BAR; PG8_SCHED;
;             PG8_LDA(At, 1, 1); PG8_STAGE(PG8_SB(1, 0), b3, voffB); PG8_STAGE(PG8_SB(1, 1), b3 + hstepB, voffB); PG8_STAGE(PG8_SA(1, 0), a3, voffA);
;             PG8_WAIT_V(8); PG8_WAIT_L(0); PG8_BAR; PG8_MMA(1, 0, At, B0); PG8_MMA(1, 1, At, B1); PG8_BAR; PG8_SCHED;
;         }
;         if (wr == 0) PG8_BAR;
	s_add_i32 s4, s51, s16
	v_lshl_add_u64 v[178:179], v[178:179], 0, s[34:35]
	s_mov_b32 m0, s4
	ds_read_b128 v[162:165], v243 offset:49152
	ds_read_b128 v[166:169], v243 offset:50176
	ds_read_b128 v[170:173], v243 offset:51200
	ds_read_b128 v[174:177], v243 offset:52224
	ds_read_b128 v[192:195], v243 offset:53248
	ds_read_b128 v[196:199], v243 offset:54272
	ds_read_b128 v[200:203], v243 offset:55296
	ds_read_b128 v[204:207], v243 offset:56320
	global_load_lds_dwordx4 v[178:179], off
	v_lshl_add_u64 v[178:179], v[208:209], 0, s[34:35]
	s_add_i32 m0, s4, 0x2000
	s_add_i32 s4, s52, s16
	global_load_lds_dwordx4 v[178:179], off
	v_lshl_add_u64 v[178:179], v[210:211], 0, s[34:35]
	s_mov_b32 m0, s4
	s_nop 0
	global_load_lds_dwordx4 v[178:179], off
	v_lshl_add_u64 v[178:179], v[212:213], 0, s[34:35]
	s_add_i32 m0, s4, 0x2000
	s_nop 0
	global_load_lds_dwordx4 v[178:179], off
	v_lshl_add_u64 v[178:179], v[214:215], 0, s[34:35]
	s_mov_b32 m0, s25
	s_nop 0
	global_load_lds_dwordx4 v[178:179], off
	v_lshl_add_u64 v[178:179], v[216:217], 0, s[34:35]
	s_mov_b32 m0, s26
	s_nop 0
	global_load_lds_dwordx4 v[178:179], off
	s_waitcnt vmcnt(8)
	s_waitcnt lgkmcnt(0)
	s_barrier
	s_setprio 1
	v_mfma_f32_16x16x32_bf16 v[62:65], v[130:133], v[162:165], v[62:65]
	v_mfma_f32_16x16x32_bf16 v[58:61], v[138:141], v[162:165], v[58:61]
	v_mfma_f32_16x16x32_bf16 v[54:57], v[130:133], v[170:173], v[54:57]
	v_mfma_f32_16x16x32_bf16 v[50:53], v[138:141], v[170:173], v[50:53]
	v_mfma_f32_16x16x32_bf16 v[46:49], v[130:133], v[192:195], v[46:49]
	v_mfma_f32_16x16x32_bf16 v[42:45], v[138:141], v[192:195], v[42:45]
	v_mfma_f32_16x16x32_bf16 v[38:41], v[130:133], v[200:203], v[38:41]
	v_mfma_f32_16x16x32_bf16 v[34:37], v[138:141], v[200:203], v[34:37]
	v_mfma_f32_16x16x32_bf16 v[62:65], v[134:137], v[166:169], v[62:65]
	v_mfma_f32_16x16x32_bf16 v[58:61], v[142:145], v[166:169], v[58:61]
	v_mfma_f32_16x16x32_bf16 v[54:57], v[134:137], v[174:177], v[54:57]
	v_mfma_f32_16x16x32_bf16 v[50:53], v[142:145], v[174:177], v[50:53]
	v_mfma_f32_16x16x32_bf16 v[46:49], v[134:137], v[196:199], v[46:49]
	v_mfma_f32_16x16x32_bf16 v[42:45], v[142:145], v[196:199], v[42:45]
	v_mfma_f32_16x16x32_bf16 v[38:41], v[134:137], v[204:207], v[38:41]
	v_mfma_f32_16x16x32_bf16 v[34:37], v[142:145], v[204:207], v[34:37]
	s_setprio 0
	s_setprio 1
	v_mfma_f32_16x16x32_bf16 v[30:33], v[146:149], v[162:165], v[30:33]
	v_mfma_f32_16x16x32_bf16 v[26:29], v[154:157], v[162:165], v[26:29]
	v_mfma_f32_16x16x32_bf16 v[22:25], v[146:149], v[170:173], v[22:25]
	v_mfma_f32_16x16x32_bf16 v[18:21], v[154:157], v[170:173], v[18:21]
	v_mfma_f32_16x16x32_bf16 v[14:17], v[146:149], v[192:195], v[14:17]
	v_mfma_f32_16x16x32_bf16 v[10:13], v[154:157], v[192:195], v[10:13]
	v_mfma_f32_16x16x32_bf16 v[6:9], v[146:149], v[200:203], v[6:9]
	v_mfma_f32_16x16x32_bf16 v[2:5], v[154:157], v[200:203], v[2:5]
	v_mfma_f32_16x16x32_bf16 v[30:33], v[150:153], v[166:169], v[30:33]
	v_mfma_f32_16x16x32_bf16 v[26:29], v[158:161], v[166:169], v[26:29]
	v_mfma_f32_16x16x32_bf16 v[22:25], v[150:153], v[174:177], v[22:25]
	v_mfma_f32_16x16x32_bf16 v[18:21], v[158:161], v[174:177], v[18:21]
	v_mfma_f32_16x16x32_bf16 v[14:17], v[150:153], v[196:199], v[14:17]
	v_mfma_f32_16x16x32_bf16 v[10:13], v[158:161], v[196:199], v[10:13]
	v_mfma_f32_16x16x32_bf16 v[6:9], v[150:153], v[204:207], v[6:9]
	v_mfma_f32_16x16x32_bf16 v[2:5], v[158:161], v[204:207], v[2:5]
	s_setprio 0
	s_barrier
	s_add_u32 s48, s48, 0x100
	s_addc_u32 s49, s49, 0
	s_add_u32 s0, s0, 0x100
	s_addc_u32 s1, s1, 0
	s_cmp_ge_u32 s50, s24
	s_mov_b32 s4, s50
	s_cbranch_scc0 .LBB0_308
	s_and_b64 vcc, exec, s[88:89]
	s_cbranch_vccz .LBB0_311
	s_barrier

; #define PG8_STAGE(bufoff, gbase, voff) do { _Pragma("unroll") for (int _i = 0; _i < 2; ++_i) \
;         __builtin_amdgcn_global_load_lds((const unsigned*)((const char*)(gbase) + (voff)[_i]), (LAS unsigned*)(lds + (bufoff) + ldsw + _i * 8192), 16, 0, 0); } while (0)
; #define PG8_LDA(dst, b, h) do { _Pragma("unroll") for (int m = 0; m < 4; ++m) _Pragma("unroll") for (int k = 0; k < 2; ++k) dst[m][k] = *(const LAS bf16x8*)(lds + PG8_SA(b, h) + aoff + m * 2048 + k * 1024); } while (0)
; #define PG8_LDB(dst, b, h) do { _Pragma("unroll") for (int n = 0; n < 2; ++n) _Pragma("unroll") for (int k = 0; k < 2; ++k) dst[n][k] = *(const LAS bf16x8*)(lds + PG8_SB(b, h) + boff + n * 2048 + k * 1024); } while (0)
; #define PG8_MMA(ai, bj, At, Bt) do { __builtin_amdgcn_s_setprio(1); _Pragma("unroll") for (int m = 0; m < 4; ++m) _Pragma("unroll") for (int n = 0; n < 2; ++n) _Pragma("unroll") for (int k = 0; k < 2; ++k) \
;         acc[ai][bj][m][n] = __builtin_amdgcn_mfma_f32_16x16x32_bf16(Bt[n][k], At[m][k], acc[ai][bj][m][n], 0, 0, 0); __builtin_amdgcn_s_setprio(0); } while (0)
; #define PG8_WAIT_V(n) asm volatile("s_waitcnt vmcnt(" #n ")" ::: "memory")
; #define PG8_WAIT_L(n) asm volatile("s_waitcnt lgkmcnt(" #n ")" ::: "memory")
; #define PG8_BAR __builtin_amdgcn_s_barrier()
; template <class Epi>
; __device__ __forceinline__ void gemm_phase(LAS unsigned char* lds, const Gemm g, const StaticOrder& S, const Epi& E) {
;     ...
;             const bool last = (t == nt - 2);
;             if constexpr (Epi::PREFETCH) { if (t == 2) E.prefetch(cur, wr, wc, lane); }
;             const char* a1 = cA + (size_t)(t + 1) * kstep;
;             const char* a2 = last ? nA : cA + (size_t)(t + 2) * kstep; const char* b2 = last ? nB : cB + (size_t)(t + 2) * kstep;
;             const char* a3 = a2 + kstep; const char* b3 = b2 + kstep;
;             PG8_LDB(B0, 0, 0); PG8_LDB(B1, 0, 1); PG8_SCHED; PG8_LDA(At, 0, 0); PG8_STAGE(PG8_SA(1, 1), a1 + hstepA, voffA);
;             PG8_WAIT_V(8); PG8_WAIT_L(0); PG8_BAR; PG8_MMA(0, 0, At, B0); PG8_MMA(0, 1, At, B1); PG8_BAR; PG8_SCHED;
;             PG8_LDA(At, 0, 1); PG8_STAGE(PG8_SB(0, 0), b2, voffB); PG8_STAGE(PG8_SB(0, 1), b2 + hstepB, voffB); PG8_STAGE(PG8_SA(0, 0), a2, voffA);
;             PG8_WAIT_V(8); PG8_WAIT_L(0); PG8_BAR; PG8_MMA(1, 0, At, B0); PG8_MMA(1, 1, At, B1); PG8_BAR; PG8_SCHED;
.LBB0_355:
	s_add_u32 s42, s40, 0x100
	s_addc_u32 s43, s41, 0
	s_add_i32 s51, 0, 0x10000
	s_cmp_eq_u32 s50, 12
	s_cselect_b32 s49, s1, s43
	s_cselect_b32 s48, s5, s42
	v_add_u32_e32 v0, s51, v156
	s_cselect_b32 s45, s26, s46
	s_cselect_b32 s44, s27, s31
	s_add_i32 s52, 0, 0x14000
	ds_read_b128 v[130:133], v0
	ds_read_b128 v[134:137], v0 offset:1024
	ds_read_b128 v[150:153], v0 offset:2048
	ds_read_b128 v[158:161], v0 offset:3072
	v_add_u32_e32 v0, s52, v156
	ds_read_b128 v[162:165], v0
	ds_read_b128 v[166:169], v0 offset:1024
	ds_read_b128 v[170:173], v0 offset:2048
	ds_read_b128 v[174:177], v0 offset:3072
	v_lshl_add_u64 v[178:179], s[40:41], 0, v[148:149]
	s_add_i32 m0, s13, 0xc000
	ds_read_b128 v[182:185], v157
	ds_read_b128 v[186:189], v157 offset:1024
	ds_read_b128 v[190:193], v157 offset:2048
	ds_read_b128 v[194:197], v157 offset:3072
	ds_read_b128 v[198:201], v157 offset:4096
	ds_read_b128 v[202:205], v157 offset:5120
	ds_read_b128 v[206:209], v157 offset:6144
	ds_read_b128 v[210:213], v157 offset:7168
	global_load_lds_dwordx4 v[178:179], off
	v_lshl_add_u64 v[178:179], s[40:41], 0, v[146:147]
	s_add_i32 m0, s13, 0xe000
	s_nop 0
	global_load_lds_dwordx4 v[178:179], off
	s_waitcnt vmcnt(8)
	s_waitcnt lgkmcnt(0)
	s_barrier
	s_setprio 1
	v_mfma_f32_16x16x32_bf16 v[126:129], v[130:133], v[182:185], v[126:129]
	v_mfma_f32_16x16x32_bf16 v[122:125], v[150:153], v[182:185], v[122:125]
	v_mfma_f32_16x16x32_bf16 v[118:121], v[130:133], v[190:193], v[118:121]
	v_mfma_f32_16x16x32_bf16 v[114:117], v[150:153], v[190:193], v[114:117]
	v_mfma_f32_16x16x32_bf16 v[110:113], v[130:133], v[198:201], v[110:113]
	v_mfma_f32_16x16x32_bf16 v[106:109], v[150:153], v[198:201], v[106:109]
	v_mfma_f32_16x16x32_bf16 v[102:105], v[130:133], v[206:209], v[102:105]
	v_mfma_f32_16x16x32_bf16 v[98:101], v[150:153], v[206:209], v[98:101]
	v_mfma_f32_16x16x32_bf16 v[126:129], v[134:137], v[186:189], v[126:129]
	v_mfma_f32_16x16x32_bf16 v[122:125], v[158:161], v[186:189], v[122:125]
	v_mfma_f32_16x16x32_bf16 v[118:121], v[134:137], v[194:197], v[118:121]
	v_mfma_f32_16x16x32_bf16 v[114:117], v[158:161], v[194:197], v[114:117]
	v_mfma_f32_16x16x32_bf16 v[110:113], v[134:137], v[202:205], v[110:113]
	v_mfma_f32_16x16x32_bf16 v[106:109], v[158:161], v[202:205], v[106:109]
	v_mfma_f32_16x16x32_bf16 v[102:105], v[134:137], v[210:213], v[102:105]
	v_mfma_f32_16x16x32_bf16 v[98:101], v[158:161], v[210:213], v[98:101]
	s_setprio 0
	s_setprio 1
	v_mfma_f32_16x16x32_bf16 v[62:65], v[162:165], v[182:185], v[62:65]
	v_mfma_f32_16x16x32_bf16 v[58:61], v[170:173], v[182:185], v[58:61]
	v_mfma_f32_16x16x32_bf16 v[54:57], v[162:165], v[190:193], v[54:57]
	v_mfma_f32_16x16x32_bf16 v[50:53], v[170:173], v[190:193], v[50:53]
	v_mfma_f32_16x16x32_bf16 v[46:49], v[162:165], v[198:201], v[46:49]
	v_mfma_f32_16x16x32_bf16 v[42:45], v[170:173], v[198:201], v[42:45]
	v_mfma_f32_16x16x32_bf16 v[38:41], v[162:165], v[206:209], v[38:41]
	v_mfma_f32_16x16x32_bf16 v[34:37], v[170:173], v[206:209], v[34:37]
	v_mfma_f32_16x16x32_bf16 v[62:65], v[166:169], v[186:189], v[62:65]
	v_mfma_f32_16x16x32_bf16 v[58:61], v[174:177], v[186:189], v[58:61]
	v_mfma_f32_16x16x32_bf16 v[54:57], v[166:169], v[194:197], v[54:57]
	v_mfma_f32_16x16x32_bf16 v[50:53], v[174:177], v[194:197], v[50:53]
	v_mfma_f32_16x16x32_bf16 v[46:49], v[166:169], v[202:205], v[46:49]
	v_mfma_f32_16x16x32_bf16 v[42:45], v[174:177], v[202:205], v[42:45]
	v_mfma_f32_16x16x32_bf16 v[38:41], v[166:169], v[210:213], v[38:41]
	v_mfma_f32_16x16x32_bf16 v[34:37], v[174:177], v[210:213], v[34:37]
	s_setprio 0
	s_barrier
	s_add_i32 s40, s51, s12
	v_lshl_add_u64 v[178:179], s[44:45], 0, v[140:141]
	s_mov_b32 m0, s40
	ds_read_b128 v[182:185], v157 offset:16384
	ds_read_b128 v[186:189], v157 offset:17408
	ds_read_b128 v[190:193], v157 offset:18432
	ds_read_b128 v[194:197], v157 offset:19456
	ds_read_b128 v[198:201], v157 offset:20480
	ds_read_b128 v[202:205], v157 offset:21504
	ds_read_b128 v[206:209], v157 offset:22528
	ds_read_b128 v[210:213], v157 offset:23552
	global_load_lds_dwordx4 v[178:179], off
	s_add_i32 m0, s40, 0x2000
	s_add_u32 s40, s44, 0x40000
	v_lshl_add_u64 v[214:215], s[44:45], 0, v[144:145]
	s_addc_u32 s41, s45, 0
	s_add_i32 s51, s52, s12
	global_load_lds_dwordx4 v[214:215], off
	v_lshl_add_u64 v[216:217], s[40:41], 0, v[140:141]
	s_mov_b32 m0, s51
	v_lshl_add_u64 v[218:219], s[48:49], 0, v[142:143]
	global_load_lds_dwordx4 v[216:217], off
	v_lshl_add_u64 v[216:217], s[40:41], 0, v[144:145]
	s_add_i32 m0, s51, 0x2000
	s_nop 0
	global_load_lds_dwordx4 v[216:217], off
	v_lshl_add_u64 v[216:217], s[48:49], 0, v[138:139]
	s_mov_b32 m0, s13
	s_nop 0
	global_load_lds_dwordx4 v[216:217], off
	s_mov_b32 m0, s14
	s_nop 0
	global_load_lds_dwordx4 v[218:219], off
	s_waitcnt vmcnt(8)
	s_waitcnt lgkmcnt(0)
	s_barrier
; #define PG8_STAGE(bufoff, gbase, voff) do { _Pragma("unroll") for (int _i = 0; _i < 2; ++_i) \
;         __builtin_amdgcn_global_load_lds((const unsigned*)((const char*)(gbase) + (voff)[_i]), (LAS unsigned*)(lds + (bufoff) + ldsw + _i * 8192), 16, 0, 0); } while (0)
; #define PG8_LDA(dst, b, h) do { _Pragma("unroll") for (int m = 0; m < 4; ++m) _Pragma("unroll") for (int k = 0; k < 2; ++k) dst[m][k] = *(const LAS bf16x8*)(lds + PG8_SA(b, h) + aoff + m * 2048 + k * 1024); } while (0)
; #define PG8_LDB(dst, b, h) do { _Pragma("unroll") for (int n = 0; n < 2; ++n) _Pragma("unroll") for (int k = 0; k < 2; ++k) dst[n][k] = *(const LAS bf16x8*)(lds + PG8_SB(b, h) + boff + n * 2048 + k * 1024); } while (0)
; #define PG8_MMA(ai, bj, At, Bt) do { __builtin_amdgcn_s_setprio(1); _Pragma("unroll") for (int m = 0; m < 4; ++m) _Pragma("unroll") for (int n = 0; n < 2; ++n) _Pragma("unroll") for (int k = 0; k < 2; ++k) \
;         acc[ai][bj][m][n] = __builtin_amdgcn_mfma_f32_16x16x32_bf16(Bt[n][k], At[m][k], acc[ai][bj][m][n], 0, 0, 0); __builtin_amdgcn_s_setprio(0); } while (0)
; #define PG8_WAIT_V(n) asm volatile("s_waitcnt vmcnt(" #n ")" ::: "memory")
; #define PG8_WAIT_L(n) asm volatile("s_waitcnt lgkmcnt(" #n ")" ::: "memory")
; #define PG8_BAR __builtin_amdgcn_s_barrier()
; #define PG8_SCHED __builtin_amdgcn_sched_barrier(0)
; template <class Epi>
; __device__ __forceinline__ void gemm_phase(LAS unsigned char* lds, const Gemm g, const StaticOrder& S, const Epi& E) {
;     ...
;             PG8_WAIT_V(8); PG8_WAIT_L(0); PG8_BAR; PG8_MMA(1, 0, At, B0); PG8_MMA(1, 1, At, B1); PG8_BAR; PG8_SCHED;
;             PG8_LDB(B0, 1, 0); PG8_LDB(B1, 1, 1); PG8_SCHED; PG8_LDA(At, 1, 0); PG8_STAGE(PG8_SA(0, 1), a2 + hstepA, voffA);
;             PG8_WAIT_V(8); PG8_WAIT_L(0); PG8_BAR; PG8_MMA(0, 0, At, B0); PG8_MMA(0, 1, At, B1); PG8_BAR; PG8_SCHED;
	s_setprio 1
	v_mfma_f32_16x16x32_bf16 v[94:97], v[130:133], v[182:185], v[94:97]
	v_mfma_f32_16x16x32_bf16 v[90:93], v[150:153], v[182:185], v[90:93]
	v_mfma_f32_16x16x32_bf16 v[86:89], v[130:133], v[190:193], v[86:89]
	v_mfma_f32_16x16x32_bf16 v[82:85], v[150:153], v[190:193], v[82:85]
	v_mfma_f32_16x16x32_bf16 v[78:81], v[130:133], v[198:201], v[78:81]
	v_mfma_f32_16x16x32_bf16 v[74:77], v[150:153], v[198:201], v[74:77]
	v_mfma_f32_16x16x32_bf16 v[70:73], v[130:133], v[206:209], v[70:73]
	v_mfma_f32_16x16x32_bf16 v[66:69], v[150:153], v[206:209], v[66:69]
	v_mfma_f32_16x16x32_bf16 v[94:97], v[134:137], v[186:189], v[94:97]
	v_mfma_f32_16x16x32_bf16 v[90:93], v[158:161], v[186:189], v[90:93]
	v_mfma_f32_16x16x32_bf16 v[86:89], v[134:137], v[194:197], v[86:89]
	v_mfma_f32_16x16x32_bf16 v[82:85], v[158:161], v[194:197], v[82:85]
	v_mfma_f32_16x16x32_bf16 v[78:81], v[134:137], v[202:205], v[78:81]
	v_mfma_f32_16x16x32_bf16 v[74:77], v[158:161], v[202:205], v[74:77]
	v_mfma_f32_16x16x32_bf16 v[70:73], v[134:137], v[210:213], v[70:73]
	v_mfma_f32_16x16x32_bf16 v[66:69], v[158:161], v[210:213], v[66:69]
	s_setprio 0
	s_setprio 1
	v_mfma_f32_16x16x32_bf16 v[30:33], v[162:165], v[182:185], v[30:33]
	v_mfma_f32_16x16x32_bf16 v[26:29], v[170:173], v[182:185], v[26:29]
	v_mfma_f32_16x16x32_bf16 v[22:25], v[162:165], v[190:193], v[22:25]
	v_mfma_f32_16x16x32_bf16 v[18:21], v[170:173], v[190:193], v[18:21]
	v_mfma_f32_16x16x32_bf16 v[14:17], v[162:165], v[198:201], v[14:17]
	v_mfma_f32_16x16x32_bf16 v[10:13], v[170:173], v[198:201], v[10:13]
	v_mfma_f32_16x16x32_bf16 v[6:9], v[162:165], v[206:209], v[6:9]
	v_mfma_f32_16x16x32_bf16 v[2:5], v[170:173], v[206:209], v[2:5]
	v_mfma_f32_16x16x32_bf16 v[30:33], v[166:169], v[186:189], v[30:33]
	v_mfma_f32_16x16x32_bf16 v[26:29], v[174:177], v[186:189], v[26:29]
	v_mfma_f32_16x16x32_bf16 v[22:25], v[166:169], v[194:197], v[22:25]
	v_mfma_f32_16x16x32_bf16 v[18:21], v[174:177], v[194:197], v[18:21]
	v_mfma_f32_16x16x32_bf16 v[14:17], v[166:169], v[202:205], v[14:17]
	v_mfma_f32_16x16x32_bf16 v[10:13], v[174:177], v[202:205], v[10:13]
	v_mfma_f32_16x16x32_bf16 v[6:9], v[166:169], v[210:213], v[6:9]
	v_mfma_f32_16x16x32_bf16 v[2:5], v[174:177], v[210:213], v[2:5]
	s_setprio 0
	s_barrier
	s_add_i32 s51, 0, 0x18000
	v_add_u32_e32 v0, s51, v156
	s_add_i32 s52, 0, 0x1c000
	ds_read_b128 v[130:133], v0
	ds_read_b128 v[134:137], v0 offset:1024
	ds_read_b128 v[150:153], v0 offset:2048
	ds_read_b128 v[158:161], v0 offset:3072
	v_add_u32_e32 v0, s52, v156
	ds_read_b128 v[162:165], v0
	ds_read_b128 v[166:169], v0 offset:1024
	ds_read_b128 v[170:173], v0 offset:2048
	ds_read_b128 v[174:177], v0 offset:3072
	s_add_u32 s40, s48, 0x40000
	s_addc_u32 s41, s49, 0
	s_mov_b32 m0, s15
	v_lshl_add_u64 v[220:221], s[40:41], 0, v[138:139]
	ds_read_b128 v[182:185], v157 offset:32768
	ds_read_b128 v[186:189], v157 offset:33792
	ds_read_b128 v[190:193], v157 offset:34816
	ds_read_b128 v[194:197], v157 offset:35840
	ds_read_b128 v[198:201], v157 offset:36864
	ds_read_b128 v[202:205], v157 offset:37888
	ds_read_b128 v[206:209], v157 offset:38912
	ds_read_b128 v[210:213], v157 offset:39936
	global_load_lds_dwordx4 v[220:221], off
	v_lshl_add_u64 v[220:221], s[40:41], 0, v[142:143]
	s_mov_b32 m0, s16
	s_nop 0
	global_load_lds_dwordx4 v[220:221], off
	s_waitcnt vmcnt(8)
	s_waitcnt lgkmcnt(0)
	s_barrier
	s_setprio 1
	v_mfma_f32_16x16x32_bf16 v[126:129], v[130:133], v[182:185], v[126:129]
	v_mfma_f32_16x16x32_bf16 v[122:125], v[150:153], v[182:185], v[122:125]
	v_mfma_f32_16x16x32_bf16 v[118:121], v[130:133], v[190:193], v[118:121]
	v_mfma_f32_16x16x32_bf16 v[114:117], v[150:153], v[190:193], v[114:117]
	v_mfma_f32_16x16x32_bf16 v[110:113], v[130:133], v[198:201], v[110:113]
	v_mfma_f32_16x16x32_bf16 v[106:109], v[150:153], v[198:201], v[106:109]
	v_mfma_f32_16x16x32_bf16 v[102:105], v[130:133], v[206:209], v[102:105]
	v_mfma_f32_16x16x32_bf16 v[98:101], v[150:153], v[206:209], v[98:101]
	v_mfma_f32_16x16x32_bf16 v[126:129], v[134:137], v[186:189], v[126:129]
	v_mfma_f32_16x16x32_bf16 v[122:125], v[158:161], v[186:189], v[122:125]
	v_mfma_f32_16x16x32_bf16 v[118:121], v[134:137], v[194:197], v[118:121]
	v_mfma_f32_16x16x32_bf16 v[114:117], v[158:161], v[194:197], v[114:117]
	v_mfma_f32_16x16x32_bf16 v[110:113], v[134:137], v[202:205], v[110:113]
	v_mfma_f32_16x16x32_bf16 v[106:109], v[158:161], v[202:205], v[106:109]
	v_mfma_f32_16x16x32_bf16 v[102:105], v[134:137], v[210:213], v[102:105]
	v_mfma_f32_16x16x32_bf16 v[98:101], v[158:161], v[210:213], v[98:101]
	s_setprio 0
	s_setprio 1
	v_mfma_f32_16x16x32_bf16 v[62:65], v[162:165], v[182:185], v[62:65]
	v_mfma_f32_16x16x32_bf16 v[58:61], v[170:173], v[182:185], v[58:61]
	v_mfma_f32_16x16x32_bf16 v[54:57], v[162:165], v[190:193], v[54:57]
	v_mfma_f32_16x16x32_bf16 v[50:53], v[170:173], v[190:193], v[50:53]
	v_mfma_f32_16x16x32_bf16 v[46:49], v[162:165], v[198:201], v[46:49]
	v_mfma_f32_16x16x32_bf16 v[42:45], v[170:173], v[198:201], v[42:45]
	v_mfma_f32_16x16x32_bf16 v[38:41], v[162:165], v[206:209], v[38:41]
	v_mfma_f32_16x16x32_bf16 v[34:37], v[170:173], v[206:209], v[34:37]
	v_mfma_f32_16x16x32_bf16 v[62:65], v[166:169], v[186:189], v[62:65]
	v_mfma_f32_16x16x32_bf16 v[58:61], v[174:177], v[186:189], v[58:61]
	v_mfma_f32_16x16x32_bf16 v[54:57], v[166:169], v[194:197], v[54:57]
	v_mfma_f32_16x16x32_bf16 v[50:53], v[174:177], v[194:197], v[50:53]
	v_mfma_f32_16x16x32_bf16 v[46:49], v[166:169], v[202:205], v[46:49]
	v_mfma_f32_16x16x32_bf16 v[42:45], v[174:177], v[202:205], v[42:45]
	v_mfma_f32_16x16x32_bf16 v[38:41], v[166:169], v[210:213], v[38:41]
	v_mfma_f32_16x16x32_bf16 v[34:37], v[174:177], v[210:213], v[34:37]
	s_setprio 0
	s_barrier
; #define PG8_STAGE(bufoff, gbase, voff) do { _Pragma("unroll") for (int _i = 0; _i < 2; ++_i) \
;         __builtin_amdgcn_global_load_lds((const unsigned*)((const char*)(gbase) + (voff)[_i]), (LAS unsigned*)(lds + (bufoff) + ldsw + _i * 8192), 16, 0, 0); } while (0)
; #define PG8_LDA(dst, b, h) do { _Pragma("unroll") for (int m = 0; m < 4; ++m) _Pragma("unroll") for (int k = 0; k < 2; ++k) dst[m][k] = *(const LAS bf16x8*)(lds + PG8_SA(b, h) + aoff + m * 2048 + k * 1024); } while (0)
; #define PG8_MMA(ai, bj, At, Bt) do { __builtin_amdgcn_s_setprio(1); _Pragma("unroll") for (int m = 0; m < 4; ++m) _Pragma("unroll") for (int n = 0; n < 2; ++n) _Pragma("unroll") for (int k = 0; k < 2; ++k) \
;         acc[ai][bj][m][n] = __builtin_amdgcn_mfma_f32_16x16x32_bf16(Bt[n][k], At[m][k], acc[ai][bj][m][n], 0, 0, 0); __builtin_amdgcn_s_setprio(0); } while (0)
; #define PG8_WAIT_V(n) asm volatile("s_waitcnt vmcnt(" #n ")" ::: "memory")
; #define PG8_WAIT_L(n) asm volatile("s_waitcnt lgkmcnt(" #n ")" ::: "memory")
; #define PG8_BAR __builtin_amdgcn_s_barrier()
; #define PG8_SCHED __builtin_amdgcn_sched_barrier(0)
; template <class Epi>
; __device__ __forceinline__ void gemm_phase(LAS unsigned char* lds, const Gemm g, const StaticOrder& S, const Epi& E) {
;     ...
;             PG8_LDA(At, 1, 1); PG8_STAGE(PG8_SB(1, 0), b3, voffB); PG8_STAGE(PG8_SB(1, 1), b3 + hstepB, voffB); PG8_STAGE(PG8_SA(1, 0), a3, voffA);
;             PG8_WAIT_V(8); PG8_WAIT_L(0); PG8_BAR; PG8_MMA(1, 0, At, B0); PG8_MMA(1, 1, At, B1); PG8_BAR; PG8_SCHED;
;         }
;         if (wr == 0) PG8_BAR;
	s_add_i32 s40, s51, s12
	v_lshl_add_u64 v[178:179], v[178:179], 0, s[34:35]
	s_mov_b32 m0, s40
	ds_read_b128 v[182:185], v157 offset:49152
	ds_read_b128 v[186:189], v157 offset:50176
	ds_read_b128 v[190:193], v157 offset:51200
	ds_read_b128 v[194:197], v157 offset:52224
	ds_read_b128 v[198:201], v157 offset:53248
	ds_read_b128 v[202:205], v157 offset:54272
	ds_read_b128 v[206:209], v157 offset:55296
	ds_read_b128 v[210:213], v157 offset:56320
	global_load_lds_dwordx4 v[178:179], off
	s_add_i32 m0, s40, 0x2000
	s_add_u32 s40, s44, 0x40080
	v_lshl_add_u64 v[178:179], v[214:215], 0, s[34:35]
	s_addc_u32 s41, s45, 0
	s_add_i32 s44, s52, s12
	global_load_lds_dwordx4 v[178:179], off
	v_lshl_add_u64 v[178:179], s[40:41], 0, v[140:141]
	s_mov_b32 m0, s44
	s_nop 0
	global_load_lds_dwordx4 v[178:179], off
	v_lshl_add_u64 v[178:179], s[40:41], 0, v[144:145]
	s_add_i32 m0, s44, 0x2000
	s_nop 0
	global_load_lds_dwordx4 v[178:179], off
	v_lshl_add_u64 v[178:179], v[216:217], 0, s[34:35]
	s_mov_b32 m0, s18
	s_nop 0
	global_load_lds_dwordx4 v[178:179], off
	v_lshl_add_u64 v[178:179], v[218:219], 0, s[34:35]
	s_mov_b32 m0, s19
	s_nop 0
	global_load_lds_dwordx4 v[178:179], off
	s_waitcnt vmcnt(8)
	s_waitcnt lgkmcnt(0)
	s_barrier
	s_setprio 1
	v_mfma_f32_16x16x32_bf16 v[94:97], v[130:133], v[182:185], v[94:97]
	v_mfma_f32_16x16x32_bf16 v[90:93], v[150:153], v[182:185], v[90:93]
	v_mfma_f32_16x16x32_bf16 v[86:89], v[130:133], v[190:193], v[86:89]
	v_mfma_f32_16x16x32_bf16 v[82:85], v[150:153], v[190:193], v[82:85]
	v_mfma_f32_16x16x32_bf16 v[78:81], v[130:133], v[198:201], v[78:81]
	v_mfma_f32_16x16x32_bf16 v[74:77], v[150:153], v[198:201], v[74:77]
	v_mfma_f32_16x16x32_bf16 v[70:73], v[130:133], v[206:209], v[70:73]
	v_mfma_f32_16x16x32_bf16 v[66:69], v[150:153], v[206:209], v[66:69]
	v_mfma_f32_16x16x32_bf16 v[94:97], v[134:137], v[186:189], v[94:97]
	v_mfma_f32_16x16x32_bf16 v[90:93], v[158:161], v[186:189], v[90:93]
	v_mfma_f32_16x16x32_bf16 v[86:89], v[134:137], v[194:197], v[86:89]
	v_mfma_f32_16x16x32_bf16 v[82:85], v[158:161], v[194:197], v[82:85]
	v_mfma_f32_16x16x32_bf16 v[78:81], v[134:137], v[202:205], v[78:81]
	v_mfma_f32_16x16x32_bf16 v[74:77], v[158:161], v[202:205], v[74:77]
	v_mfma_f32_16x16x32_bf16 v[70:73], v[134:137], v[210:213], v[70:73]
	v_mfma_f32_16x16x32_bf16 v[66:69], v[158:161], v[210:213], v[66:69]
	s_setprio 0
	s_setprio 1
	v_mfma_f32_16x16x32_bf16 v[30:33], v[162:165], v[182:185], v[30:33]
	v_mfma_f32_16x16x32_bf16 v[26:29], v[170:173], v[182:185], v[26:29]
	v_mfma_f32_16x16x32_bf16 v[22:25], v[162:165], v[190:193], v[22:25]
	v_mfma_f32_16x16x32_bf16 v[18:21], v[170:173], v[190:193], v[18:21]
	v_mfma_f32_16x16x32_bf16 v[14:17], v[162:165], v[198:201], v[14:17]
	v_mfma_f32_16x16x32_bf16 v[10:13], v[170:173], v[198:201], v[10:13]
	v_mfma_f32_16x16x32_bf16 v[6:9], v[162:165], v[206:209], v[6:9]
	v_mfma_f32_16x16x32_bf16 v[2:5], v[170:173], v[206:209], v[2:5]
	v_mfma_f32_16x16x32_bf16 v[30:33], v[166:169], v[186:189], v[30:33]
	v_mfma_f32_16x16x32_bf16 v[26:29], v[174:177], v[186:189], v[26:29]
	v_mfma_f32_16x16x32_bf16 v[22:25], v[166:169], v[194:197], v[22:25]
	v_mfma_f32_16x16x32_bf16 v[18:21], v[174:177], v[194:197], v[18:21]
	v_mfma_f32_16x16x32_bf16 v[14:17], v[166:169], v[202:205], v[14:17]
	v_mfma_f32_16x16x32_bf16 v[10:13], v[174:177], v[202:205], v[10:13]
	v_mfma_f32_16x16x32_bf16 v[6:9], v[166:169], v[210:213], v[6:9]
	v_mfma_f32_16x16x32_bf16 v[2:5], v[174:177], v[210:213], v[2:5]
	s_setprio 0
	s_barrier
	s_add_i32 s50, s50, 2
	s_add_u32 s31, s31, 0x100
	s_addc_u32 s46, s46, 0
	s_cmp_gt_u32 s50, 13
	s_mov_b64 s[40:41], s[42:43]
	s_cbranch_scc0 .LBB0_355
	s_and_b64 vcc, exec, s[82:83]
	s_cbranch_vccz .LBB0_358
	s_barrier

; #define PG8_STAGE(bufoff, gbase, voff) do { _Pragma("unroll") for (int _i = 0; _i < 2; ++_i) \
;         __builtin_amdgcn_global_load_lds((const unsigned*)((const char*)(gbase) + (voff)[_i]), (LAS unsigned*)(lds + (bufoff) + ldsw + _i * 8192), 16, 0, 0); } while (0)
; #define PG8_LDA(dst, b, h) do { _Pragma("unroll") for (int m = 0; m < 4; ++m) _Pragma("unroll") for (int k = 0; k < 2; ++k) dst[m][k] = *(const LAS bf16x8*)(lds + PG8_SA(b, h) + aoff + m * 2048 + k * 1024); } while (0)
; #define PG8_LDB(dst, b, h) do { _Pragma("unroll") for (int n = 0; n < 2; ++n) _Pragma("unroll") for (int k = 0; k < 2; ++k) dst[n][k] = *(const LAS bf16x8*)(lds + PG8_SB(b, h) + boff + n * 2048 + k * 1024); } while (0)
; #define PG8_MMA(ai, bj, At, Bt) do { __builtin_amdgcn_s_setprio(1); _Pragma("unroll") for (int m = 0; m < 4; ++m) _Pragma("unroll") for (int n = 0; n < 2; ++n) _Pragma("unroll") for (int k = 0; k < 2; ++k) \
;         acc[ai][bj][m][n] = __builtin_amdgcn_mfma_f32_16x16x32_bf16(Bt[n][k], At[m][k], acc[ai][bj][m][n], 0, 0, 0); __builtin_amdgcn_s_setprio(0); } while (0)
; #define PG8_WAIT_V(n) asm volatile("s_waitcnt vmcnt(" #n ")" ::: "memory")
; #define PG8_WAIT_L(n) asm volatile("s_waitcnt lgkmcnt(" #n ")" ::: "memory")
; #define PG8_BAR __builtin_amdgcn_s_barrier()
; template <class Epi>
; __device__ __forceinline__ void gemm_phase(LAS unsigned char* lds, const Gemm g, const StaticOrder& S, const Epi& E) {
;     ...
;             const bool last = (t == nt - 2);
;             if constexpr (Epi::PREFETCH) { if (t == 2) E.prefetch(cur, wr, wc, lane); }
;             const char* a1 = cA + (size_t)(t + 1) * kstep;
;             const char* a2 = last ? nA : cA + (size_t)(t + 2) * kstep; const char* b2 = last ? nB : cB + (size_t)(t + 2) * kstep;
;             const char* a3 = a2 + kstep; const char* b3 = b2 + kstep;
;             PG8_LDB(B0, 0, 0); PG8_LDB(B1, 0, 1); PG8_SCHED; PG8_LDA(At, 0, 0); PG8_STAGE(PG8_SA(1, 1), a1 + hstepA, voffA);
;             PG8_WAIT_V(8); PG8_WAIT_L(0); PG8_BAR; PG8_MMA(0, 0, At, B0); PG8_MMA(0, 1, At, B1); PG8_BAR; PG8_SCHED;
;             PG8_LDA(At, 0, 1); PG8_STAGE(PG8_SB(0, 0), b2, voffB); PG8_STAGE(PG8_SB(0, 1), b2 + hstepB, voffB); PG8_STAGE(PG8_SA(0, 0), a2, voffA);
;             PG8_WAIT_V(8); PG8_WAIT_L(0); PG8_BAR; PG8_MMA(1, 0, At, B0); PG8_MMA(1, 1, At, B1); PG8_BAR; PG8_SCHED;
.LBB0_729:
	s_add_u32 s0, s4, s6
	s_addc_u32 s1, s5, s7
	s_add_u32 s0, s0, 0x100
	s_addc_u32 s1, s1, 0
	s_add_u32 s48, s54, s6
	s_addc_u32 s49, s55, s7
	s_add_i32 s50, 0, 0x10000
	s_cmpk_eq_i32 s6, 0x700
	s_cselect_b32 s9, s27, s1
	s_cselect_b32 s8, s31, s0
	v_add_u32_e32 v144, s50, v149
	s_cselect_b32 s1, s45, s49
	s_cselect_b32 s0, s52, s48
	s_add_i32 s51, 0, 0x14000
	ds_read_b128 v[152:155], v144
	ds_read_b128 v[156:159], v144 offset:1024
	ds_read_b128 v[160:163], v144 offset:2048
	ds_read_b128 v[164:167], v144 offset:3072
	v_add_u32_e32 v144, s51, v149
	ds_read_b128 v[168:171], v144
	ds_read_b128 v[172:175], v144 offset:1024
	ds_read_b128 v[176:179], v144 offset:2048
	ds_read_b128 v[182:185], v144 offset:3072
	v_lshl_add_u64 v[144:145], v[142:143], 0, s[6:7]
	s_add_i32 m0, s15, 0xc000
	ds_read_b128 v[186:189], v150
	ds_read_b128 v[190:193], v150 offset:1024
	ds_read_b128 v[194:197], v150 offset:2048
	ds_read_b128 v[198:201], v150 offset:3072
	ds_read_b128 v[202:205], v150 offset:4096
	ds_read_b128 v[206:209], v150 offset:5120
	ds_read_b128 v[210:213], v150 offset:6144
	ds_read_b128 v[214:217], v150 offset:7168
	global_load_lds_dwordx4 v[144:145], off
	v_lshl_add_u64 v[144:145], v[140:141], 0, s[6:7]
	s_add_i32 m0, s15, 0xe000
	s_nop 0
	global_load_lds_dwordx4 v[144:145], off
	s_waitcnt vmcnt(8)
	s_waitcnt lgkmcnt(0)
	s_barrier
	s_setprio 1
	v_mfma_f32_16x16x32_bf16 v[126:129], v[152:155], v[186:189], v[126:129]
	v_mfma_f32_16x16x32_bf16 v[82:85], v[160:163], v[186:189], v[82:85]
	v_mfma_f32_16x16x32_bf16 v[122:125], v[152:155], v[194:197], v[122:125]
	v_mfma_f32_16x16x32_bf16 v[86:89], v[160:163], v[194:197], v[86:89]
	v_mfma_f32_16x16x32_bf16 v[118:121], v[152:155], v[202:205], v[118:121]
	v_mfma_f32_16x16x32_bf16 v[90:93], v[160:163], v[202:205], v[90:93]
	v_mfma_f32_16x16x32_bf16 v[114:117], v[152:155], v[210:213], v[114:117]
	v_mfma_f32_16x16x32_bf16 v[94:97], v[160:163], v[210:213], v[94:97]
	v_mfma_f32_16x16x32_bf16 v[126:129], v[156:159], v[190:193], v[126:129]
	v_mfma_f32_16x16x32_bf16 v[82:85], v[164:167], v[190:193], v[82:85]
	v_mfma_f32_16x16x32_bf16 v[122:125], v[156:159], v[198:201], v[122:125]
	v_mfma_f32_16x16x32_bf16 v[86:89], v[164:167], v[198:201], v[86:89]
	v_mfma_f32_16x16x32_bf16 v[118:121], v[156:159], v[206:209], v[118:121]
	v_mfma_f32_16x16x32_bf16 v[90:93], v[164:167], v[206:209], v[90:93]
	v_mfma_f32_16x16x32_bf16 v[114:117], v[156:159], v[214:217], v[114:117]
	v_mfma_f32_16x16x32_bf16 v[94:97], v[164:167], v[214:217], v[94:97]
	s_setprio 0
	s_setprio 1
	v_mfma_f32_16x16x32_bf16 v[110:113], v[168:171], v[186:189], v[110:113]
	v_mfma_f32_16x16x32_bf16 v[66:69], v[176:179], v[186:189], v[66:69]
	v_mfma_f32_16x16x32_bf16 v[106:109], v[168:171], v[194:197], v[106:109]
	v_mfma_f32_16x16x32_bf16 v[70:73], v[176:179], v[194:197], v[70:73]
	v_mfma_f32_16x16x32_bf16 v[102:105], v[168:171], v[202:205], v[102:105]
	v_mfma_f32_16x16x32_bf16 v[74:77], v[176:179], v[202:205], v[74:77]
	v_mfma_f32_16x16x32_bf16 v[98:101], v[168:171], v[210:213], v[98:101]
	v_mfma_f32_16x16x32_bf16 v[78:81], v[176:179], v[210:213], v[78:81]
	v_mfma_f32_16x16x32_bf16 v[110:113], v[172:175], v[190:193], v[110:113]
	v_mfma_f32_16x16x32_bf16 v[66:69], v[182:185], v[190:193], v[66:69]
	v_mfma_f32_16x16x32_bf16 v[106:109], v[172:175], v[198:201], v[106:109]
	v_mfma_f32_16x16x32_bf16 v[70:73], v[182:185], v[198:201], v[70:73]
	v_mfma_f32_16x16x32_bf16 v[102:105], v[172:175], v[206:209], v[102:105]
	v_mfma_f32_16x16x32_bf16 v[74:77], v[182:185], v[206:209], v[74:77]
	v_mfma_f32_16x16x32_bf16 v[98:101], v[172:175], v[214:217], v[98:101]
	v_mfma_f32_16x16x32_bf16 v[78:81], v[182:185], v[214:217], v[78:81]
	s_setprio 0
	s_barrier
	s_add_i32 s48, s50, s14
	v_lshl_add_u64 v[144:145], s[0:1], 0, v[0:1]
	s_mov_b32 m0, s48
	ds_read_b128 v[186:189], v150 offset:16384
	ds_read_b128 v[190:193], v150 offset:17408
	ds_read_b128 v[194:197], v150 offset:18432
	ds_read_b128 v[198:201], v150 offset:19456
	ds_read_b128 v[202:205], v150 offset:20480
	ds_read_b128 v[206:209], v150 offset:21504
	ds_read_b128 v[210:213], v150 offset:22528
	ds_read_b128 v[214:217], v150 offset:23552
	global_load_lds_dwordx4 v[144:145], off
	s_add_i32 m0, s48, 0x2000
	s_add_u32 s48, s0, 0x40000
	v_lshl_add_u64 v[218:219], s[0:1], 0, v[134:135]
	s_addc_u32 s49, s1, 0
	s_add_i32 s50, s51, s14
	global_load_lds_dwordx4 v[218:219], off
	v_lshl_add_u64 v[220:221], s[48:49], 0, v[0:1]
	s_mov_b32 m0, s50
	v_lshl_add_u64 v[222:223], s[8:9], 0, v[132:133]
	global_load_lds_dwordx4 v[220:221], off
	v_lshl_add_u64 v[220:221], s[48:49], 0, v[134:135]
	s_add_i32 m0, s50, 0x2000
	s_nop 0
	global_load_lds_dwordx4 v[220:221], off
	v_lshl_add_u64 v[220:221], s[8:9], 0, v[130:131]
	s_mov_b32 m0, s15
	s_nop 0
	global_load_lds_dwordx4 v[220:221], off
	s_mov_b32 m0, s16
	s_nop 0
	global_load_lds_dwordx4 v[222:223], off
	s_waitcnt vmcnt(8)
	s_waitcnt lgkmcnt(0)
	s_barrier
; #define PG8_STAGE(bufoff, gbase, voff) do { _Pragma("unroll") for (int _i = 0; _i < 2; ++_i) \
;         __builtin_amdgcn_global_load_lds((const unsigned*)((const char*)(gbase) + (voff)[_i]), (LAS unsigned*)(lds + (bufoff) + ldsw + _i * 8192), 16, 0, 0); } while (0)
; #define PG8_LDA(dst, b, h) do { _Pragma("unroll") for (int m = 0; m < 4; ++m) _Pragma("unroll") for (int k = 0; k < 2; ++k) dst[m][k] = *(const LAS bf16x8*)(lds + PG8_SA(b, h) + aoff + m * 2048 + k * 1024); } while (0)
; #define PG8_LDB(dst, b, h) do { _Pragma("unroll") for (int n = 0; n < 2; ++n) _Pragma("unroll") for (int k = 0; k < 2; ++k) dst[n][k] = *(const LAS bf16x8*)(lds + PG8_SB(b, h) + boff + n * 2048 + k * 1024); } while (0)
; #define PG8_MMA(ai, bj, At, Bt) do { __builtin_amdgcn_s_setprio(1); _Pragma("unroll") for (int m = 0; m < 4; ++m) _Pragma("unroll") for (int n = 0; n < 2; ++n) _Pragma("unroll") for (int k = 0; k < 2; ++k) \
;         acc[ai][bj][m][n] = __builtin_amdgcn_mfma_f32_16x16x32_bf16(Bt[n][k], At[m][k], acc[ai][bj][m][n], 0, 0, 0); __builtin_amdgcn_s_setprio(0); } while (0)
; #define PG8_WAIT_V(n) asm volatile("s_waitcnt vmcnt(" #n ")" ::: "memory")
; #define PG8_WAIT_L(n) asm volatile("s_waitcnt lgkmcnt(" #n ")" ::: "memory")
; #define PG8_BAR __builtin_amdgcn_s_barrier()
; #define PG8_SCHED __builtin_amdgcn_sched_barrier(0)
; template <class Epi>
; __device__ __forceinline__ void gemm_phase(LAS unsigned char* lds, const Gemm g, const StaticOrder& S, const Epi& E) {
;     ...
;             PG8_WAIT_V(8); PG8_WAIT_L(0); PG8_BAR; PG8_MMA(1, 0, At, B0); PG8_MMA(1, 1, At, B1); PG8_BAR; PG8_SCHED;
;             PG8_LDB(B0, 1, 0); PG8_LDB(B1, 1, 1); PG8_SCHED; PG8_LDA(At, 1, 0); PG8_STAGE(PG8_SA(0, 1), a2 + hstepA, voffA);
;             PG8_WAIT_V(8); PG8_WAIT_L(0); PG8_BAR; PG8_MMA(0, 0, At, B0); PG8_MMA(0, 1, At, B1); PG8_BAR; PG8_SCHED;
	s_setprio 1
	v_mfma_f32_16x16x32_bf16 v[62:65], v[152:155], v[186:189], v[62:65]
	v_mfma_f32_16x16x32_bf16 v[18:21], v[160:163], v[186:189], v[18:21]
	v_mfma_f32_16x16x32_bf16 v[58:61], v[152:155], v[194:197], v[58:61]
	v_mfma_f32_16x16x32_bf16 v[22:25], v[160:163], v[194:197], v[22:25]
	v_mfma_f32_16x16x32_bf16 v[54:57], v[152:155], v[202:205], v[54:57]
	v_mfma_f32_16x16x32_bf16 v[26:29], v[160:163], v[202:205], v[26:29]
	v_mfma_f32_16x16x32_bf16 v[50:53], v[152:155], v[210:213], v[50:53]
	v_mfma_f32_16x16x32_bf16 v[30:33], v[160:163], v[210:213], v[30:33]
	v_mfma_f32_16x16x32_bf16 v[62:65], v[156:159], v[190:193], v[62:65]
	v_mfma_f32_16x16x32_bf16 v[18:21], v[164:167], v[190:193], v[18:21]
	v_mfma_f32_16x16x32_bf16 v[58:61], v[156:159], v[198:201], v[58:61]
	v_mfma_f32_16x16x32_bf16 v[22:25], v[164:167], v[198:201], v[22:25]
	v_mfma_f32_16x16x32_bf16 v[54:57], v[156:159], v[206:209], v[54:57]
	v_mfma_f32_16x16x32_bf16 v[26:29], v[164:167], v[206:209], v[26:29]
	v_mfma_f32_16x16x32_bf16 v[50:53], v[156:159], v[214:217], v[50:53]
	v_mfma_f32_16x16x32_bf16 v[30:33], v[164:167], v[214:217], v[30:33]
	s_setprio 0
	s_setprio 1
	v_mfma_f32_16x16x32_bf16 v[46:49], v[168:171], v[186:189], v[46:49]
	v_mfma_f32_16x16x32_bf16 v[2:5], v[176:179], v[186:189], v[2:5]
	v_mfma_f32_16x16x32_bf16 v[42:45], v[168:171], v[194:197], v[42:45]
	v_mfma_f32_16x16x32_bf16 v[6:9], v[176:179], v[194:197], v[6:9]
	v_mfma_f32_16x16x32_bf16 v[38:41], v[168:171], v[202:205], v[38:41]
	v_mfma_f32_16x16x32_bf16 v[10:13], v[176:179], v[202:205], v[10:13]
	v_mfma_f32_16x16x32_bf16 v[34:37], v[168:171], v[210:213], v[34:37]
	v_mfma_f32_16x16x32_bf16 v[14:17], v[176:179], v[210:213], v[14:17]
	v_mfma_f32_16x16x32_bf16 v[46:49], v[172:175], v[190:193], v[46:49]
	v_mfma_f32_16x16x32_bf16 v[2:5], v[182:185], v[190:193], v[2:5]
	v_mfma_f32_16x16x32_bf16 v[42:45], v[172:175], v[198:201], v[42:45]
	v_mfma_f32_16x16x32_bf16 v[6:9], v[182:185], v[198:201], v[6:9]
	v_mfma_f32_16x16x32_bf16 v[38:41], v[172:175], v[206:209], v[38:41]
	v_mfma_f32_16x16x32_bf16 v[10:13], v[182:185], v[206:209], v[10:13]
	v_mfma_f32_16x16x32_bf16 v[34:37], v[172:175], v[214:217], v[34:37]
	v_mfma_f32_16x16x32_bf16 v[14:17], v[182:185], v[214:217], v[14:17]
	s_setprio 0
	s_barrier
	s_add_i32 s48, 0, 0x18000
	v_add_u32_e32 v151, s48, v149
	s_add_i32 s49, 0, 0x1c000
	ds_read_b128 v[152:155], v151
	ds_read_b128 v[156:159], v151 offset:1024
	ds_read_b128 v[160:163], v151 offset:2048
	ds_read_b128 v[164:167], v151 offset:3072
	v_add_u32_e32 v151, s49, v149
	ds_read_b128 v[168:171], v151
	ds_read_b128 v[172:175], v151 offset:1024
	ds_read_b128 v[176:179], v151 offset:2048
	ds_read_b128 v[182:185], v151 offset:3072
	s_add_u32 s8, s8, 0x40000
	s_addc_u32 s9, s9, 0
	s_mov_b32 m0, s17
	v_lshl_add_u64 v[224:225], s[8:9], 0, v[130:131]
	ds_read_b128 v[186:189], v150 offset:32768
	ds_read_b128 v[190:193], v150 offset:33792
	ds_read_b128 v[194:197], v150 offset:34816
	ds_read_b128 v[198:201], v150 offset:35840
	ds_read_b128 v[202:205], v150 offset:36864
	ds_read_b128 v[206:209], v150 offset:37888
	ds_read_b128 v[210:213], v150 offset:38912
	ds_read_b128 v[214:217], v150 offset:39936
	global_load_lds_dwordx4 v[224:225], off
	v_lshl_add_u64 v[224:225], s[8:9], 0, v[132:133]
	s_mov_b32 m0, s18
	s_nop 0
	global_load_lds_dwordx4 v[224:225], off
	s_waitcnt vmcnt(8)
	s_waitcnt lgkmcnt(0)
	s_barrier
	s_setprio 1
	v_mfma_f32_16x16x32_bf16 v[126:129], v[152:155], v[186:189], v[126:129]
	v_mfma_f32_16x16x32_bf16 v[82:85], v[160:163], v[186:189], v[82:85]
	v_mfma_f32_16x16x32_bf16 v[122:125], v[152:155], v[194:197], v[122:125]
	v_mfma_f32_16x16x32_bf16 v[86:89], v[160:163], v[194:197], v[86:89]
	v_mfma_f32_16x16x32_bf16 v[118:121], v[152:155], v[202:205], v[118:121]
	v_mfma_f32_16x16x32_bf16 v[90:93], v[160:163], v[202:205], v[90:93]
	v_mfma_f32_16x16x32_bf16 v[114:117], v[152:155], v[210:213], v[114:117]
	v_mfma_f32_16x16x32_bf16 v[94:97], v[160:163], v[210:213], v[94:97]
	v_mfma_f32_16x16x32_bf16 v[126:129], v[156:159], v[190:193], v[126:129]
	v_mfma_f32_16x16x32_bf16 v[82:85], v[164:167], v[190:193], v[82:85]
	v_mfma_f32_16x16x32_bf16 v[122:125], v[156:159], v[198:201], v[122:125]
	v_mfma_f32_16x16x32_bf16 v[86:89], v[164:167], v[198:201], v[86:89]
	v_mfma_f32_16x16x32_bf16 v[118:121], v[156:159], v[206:209], v[118:121]
	v_mfma_f32_16x16x32_bf16 v[90:93], v[164:167], v[206:209], v[90:93]
	v_mfma_f32_16x16x32_bf16 v[114:117], v[156:159], v[214:217], v[114:117]
	v_mfma_f32_16x16x32_bf16 v[94:97], v[164:167], v[214:217], v[94:97]
	s_setprio 0
	s_setprio 1
	v_mfma_f32_16x16x32_bf16 v[110:113], v[168:171], v[186:189], v[110:113]
	v_mfma_f32_16x16x32_bf16 v[66:69], v[176:179], v[186:189], v[66:69]
	v_mfma_f32_16x16x32_bf16 v[106:109], v[168:171], v[194:197], v[106:109]
	v_mfma_f32_16x16x32_bf16 v[70:73], v[176:179], v[194:197], v[70:73]
	v_mfma_f32_16x16x32_bf16 v[102:105], v[168:171], v[202:205], v[102:105]
	v_mfma_f32_16x16x32_bf16 v[74:77], v[176:179], v[202:205], v[74:77]
	v_mfma_f32_16x16x32_bf16 v[98:101], v[168:171], v[210:213], v[98:101]
	v_mfma_f32_16x16x32_bf16 v[78:81], v[176:179], v[210:213], v[78:81]
	v_mfma_f32_16x16x32_bf16 v[110:113], v[172:175], v[190:193], v[110:113]
	v_mfma_f32_16x16x32_bf16 v[66:69], v[182:185], v[190:193], v[66:69]
	v_mfma_f32_16x16x32_bf16 v[106:109], v[172:175], v[198:201], v[106:109]
	v_mfma_f32_16x16x32_bf16 v[70:73], v[182:185], v[198:201], v[70:73]
	v_mfma_f32_16x16x32_bf16 v[102:105], v[172:175], v[206:209], v[102:105]
	v_mfma_f32_16x16x32_bf16 v[74:77], v[182:185], v[206:209], v[74:77]
	v_mfma_f32_16x16x32_bf16 v[98:101], v[172:175], v[214:217], v[98:101]
	v_mfma_f32_16x16x32_bf16 v[78:81], v[182:185], v[214:217], v[78:81]
	s_setprio 0
	s_barrier
; #define PG8_STAGE(bufoff, gbase, voff) do { _Pragma("unroll") for (int _i = 0; _i < 2; ++_i) \
;         __builtin_amdgcn_global_load_lds((const unsigned*)((const char*)(gbase) + (voff)[_i]), (LAS unsigned*)(lds + (bufoff) + ldsw + _i * 8192), 16, 0, 0); } while (0)
; #define PG8_LDA(dst, b, h) do { _Pragma("unroll") for (int m = 0; m < 4; ++m) _Pragma("unroll") for (int k = 0; k < 2; ++k) dst[m][k] = *(const LAS bf16x8*)(lds + PG8_SA(b, h) + aoff + m * 2048 + k * 1024); } while (0)
; #define PG8_LDB(dst, b, h) do { _Pragma("unroll") for (int n = 0; n < 2; ++n) _Pragma("unroll") for (int k = 0; k < 2; ++k) dst[n][k] = *(const LAS bf16x8*)(lds + PG8_SB(b, h) + boff + n * 2048 + k * 1024); } while (0)
; #define PG8_BAR __builtin_amdgcn_s_barrier()
; template <class Epi>
; __device__ __forceinline__ void gemm_phase(LAS unsigned char* lds, const Gemm g, const StaticOrder& S, const Epi& E) {
;     ...
;         for (int t = 0; t < nt; t += 2) {
;             const bool last = (t == nt - 2);
;             if constexpr (Epi::PREFETCH) { if (t == 2) E.prefetch(cur, wr, wc, lane); }
;             const char* a1 = cA + (size_t)(t + 1) * kstep;
;             const char* a2 = last ? nA : cA + (size_t)(t + 2) * kstep; const char* b2 = last ? nB : cB + (size_t)(t + 2) * kstep;
;             const char* a3 = a2 + kstep; const char* b3 = b2 + kstep;
;             PG8_LDB(B0, 0, 0); PG8_LDB(B1, 0, 1); PG8_SCHED; PG8_LDA(At, 0, 0); PG8_STAGE(PG8_SA(1, 1), a1 + hstepA, voffA);
;             PG8_WAIT_V(8); PG8_WAIT_L(0); PG8_BAR; PG8_MMA(0, 0, At, B0); PG8_MMA(0, 1, At, B1); PG8_BAR; PG8_SCHED;
;             PG8_LDA(At, 0, 1); PG8_STAGE(PG8_SB(0, 0), b2, voffB); PG8_STAGE(PG8_SB(0, 1), b2 + hstepB, voffB); PG8_STAGE(PG8_SA(0, 0), a2, voffA);
;             PG8_WAIT_V(8); PG8_WAIT_L(0); PG8_BAR; PG8_MMA(1, 0, At, B0); PG8_MMA(1, 1, At, B1); PG8_BAR; PG8_SCHED;
;             PG8_LDB(B0, 1, 0); PG8_LDB(B1, 1, 1); PG8_SCHED; PG8_LDA(At, 1, 0); PG8_STAGE(PG8_SA(0, 1), a2 + hstepA, voffA);
;             PG8_WAIT_V(8); PG8_WAIT_L(0); PG8_BAR; PG8_MMA(0, 0, At, B0); PG8_MMA(0, 1, At, B1); PG8_BAR; PG8_SCHED;
;             PG8_LDA(At, 1, 1); PG8_STAGE(PG8_SB(1, 0), b3, voffB); PG8_STAGE(PG8_SB(1, 1), b3 + hstepB, voffB); PG8_STAGE(PG8_SA(1, 0), a3, voffA);
;             PG8_WAIT_V(8); PG8_WAIT_L(0); PG8_BAR; PG8_MMA(1, 0, At, B0); PG8_MMA(1, 1, At, B1); PG8_BAR; PG8_SCHED;
;         }
	s_add_i32 s8, s48, s14
	v_lshl_add_u64 v[144:145], v[144:145], 0, s[34:35]
	s_mov_b32 m0, s8
	ds_read_b128 v[186:189], v150 offset:49152
	ds_read_b128 v[190:193], v150 offset:50176
	ds_read_b128 v[194:197], v150 offset:51200
	ds_read_b128 v[198:201], v150 offset:52224
	ds_read_b128 v[202:205], v150 offset:53248
	ds_read_b128 v[206:209], v150 offset:54272
	ds_read_b128 v[210:213], v150 offset:55296
	ds_read_b128 v[214:217], v150 offset:56320
	global_load_lds_dwordx4 v[144:145], off
	s_add_i32 m0, s8, 0x2000
	s_add_u32 s0, s0, 0x40080
	v_lshl_add_u64 v[144:145], v[218:219], 0, s[34:35]
	s_addc_u32 s1, s1, 0
	s_add_i32 s8, s49, s14
	global_load_lds_dwordx4 v[144:145], off
	v_lshl_add_u64 v[144:145], s[0:1], 0, v[0:1]
	s_mov_b32 m0, s8
	s_nop 0
	global_load_lds_dwordx4 v[144:145], off
	v_lshl_add_u64 v[144:145], s[0:1], 0, v[134:135]
	s_add_i32 m0, s8, 0x2000
	s_nop 0
	global_load_lds_dwordx4 v[144:145], off
	v_lshl_add_u64 v[144:145], v[220:221], 0, s[34:35]
	s_mov_b32 m0, s21
	s_nop 0
	global_load_lds_dwordx4 v[144:145], off
	v_lshl_add_u64 v[144:145], v[222:223], 0, s[34:35]
	s_mov_b32 m0, s22
	s_nop 0
	global_load_lds_dwordx4 v[144:145], off
	s_waitcnt vmcnt(8)
	s_waitcnt lgkmcnt(0)
	s_barrier
	s_setprio 1
	v_mfma_f32_16x16x32_bf16 v[62:65], v[152:155], v[186:189], v[62:65]
	v_mfma_f32_16x16x32_bf16 v[18:21], v[160:163], v[186:189], v[18:21]
	v_mfma_f32_16x16x32_bf16 v[58:61], v[152:155], v[194:197], v[58:61]
	v_mfma_f32_16x16x32_bf16 v[22:25], v[160:163], v[194:197], v[22:25]
	v_mfma_f32_16x16x32_bf16 v[54:57], v[152:155], v[202:205], v[54:57]
	v_mfma_f32_16x16x32_bf16 v[26:29], v[160:163], v[202:205], v[26:29]
	v_mfma_f32_16x16x32_bf16 v[50:53], v[152:155], v[210:213], v[50:53]
	v_mfma_f32_16x16x32_bf16 v[30:33], v[160:163], v[210:213], v[30:33]
	v_mfma_f32_16x16x32_bf16 v[62:65], v[156:159], v[190:193], v[62:65]
	v_mfma_f32_16x16x32_bf16 v[18:21], v[164:167], v[190:193], v[18:21]
	v_mfma_f32_16x16x32_bf16 v[58:61], v[156:159], v[198:201], v[58:61]
	v_mfma_f32_16x16x32_bf16 v[22:25], v[164:167], v[198:201], v[22:25]
	v_mfma_f32_16x16x32_bf16 v[54:57], v[156:159], v[206:209], v[54:57]
	v_mfma_f32_16x16x32_bf16 v[26:29], v[164:167], v[206:209], v[26:29]
	v_mfma_f32_16x16x32_bf16 v[50:53], v[156:159], v[214:217], v[50:53]
	v_mfma_f32_16x16x32_bf16 v[30:33], v[164:167], v[214:217], v[30:33]
	s_setprio 0
	s_setprio 1
	v_mfma_f32_16x16x32_bf16 v[46:49], v[168:171], v[186:189], v[46:49]
	v_mfma_f32_16x16x32_bf16 v[2:5], v[176:179], v[186:189], v[2:5]
	v_mfma_f32_16x16x32_bf16 v[42:45], v[168:171], v[194:197], v[42:45]
	v_mfma_f32_16x16x32_bf16 v[6:9], v[176:179], v[194:197], v[6:9]
	v_mfma_f32_16x16x32_bf16 v[38:41], v[168:171], v[202:205], v[38:41]
	v_mfma_f32_16x16x32_bf16 v[10:13], v[176:179], v[202:205], v[10:13]
	v_mfma_f32_16x16x32_bf16 v[34:37], v[168:171], v[210:213], v[34:37]
	v_mfma_f32_16x16x32_bf16 v[14:17], v[176:179], v[210:213], v[14:17]
	v_mfma_f32_16x16x32_bf16 v[46:49], v[172:175], v[190:193], v[46:49]
	v_mfma_f32_16x16x32_bf16 v[2:5], v[182:185], v[190:193], v[2:5]
	v_mfma_f32_16x16x32_bf16 v[42:45], v[172:175], v[198:201], v[42:45]
	v_mfma_f32_16x16x32_bf16 v[6:9], v[182:185], v[198:201], v[6:9]
	v_mfma_f32_16x16x32_bf16 v[38:41], v[172:175], v[206:209], v[38:41]
	v_mfma_f32_16x16x32_bf16 v[10:13], v[182:185], v[206:209], v[10:13]
	v_mfma_f32_16x16x32_bf16 v[34:37], v[172:175], v[214:217], v[34:37]
	v_mfma_f32_16x16x32_bf16 v[14:17], v[182:185], v[214:217], v[14:17]
	s_setprio 0
	s_barrier
	s_add_i32 s56, s56, 2
	s_add_u32 s6, s6, 0x100
	s_addc_u32 s7, s7, 0
	s_cmp_gt_u32 s56, 13
	s_cbranch_scc1 .LBB0_771
